# de-serialised GEMM epilogue loads (EpiRes/EpiGlu): same-base src loads issued together, one wait per row block
# speedup vs baseline: 1.0359x; 1.0150x over previous
.LBB0_838:
	s_or_b64 exec, exec, s[8:9]
	v_add_u32_e32 v166, s3, v165
	v_ashrrev_i32_e32 v167, 31, v166
	v_lshlrev_b64 v[170:171], 2, v[166:167]
	v_lshl_add_u64 v[172:173], v[160:161], 0, v[170:171]
	global_load_dwordx4 v[166:169], v[172:173], off
	global_load_dwordx4 v[176:179], v[172:173], off offset:64
	global_load_dwordx4 v[180:183], v[172:173], off offset:512
	global_load_dwordx4 v[184:187], v[172:173], off offset:576
	v_readlane_b32 s8, v255, 10
	v_readlane_b32 s9, v255, 11
	s_waitcnt vmcnt(0) lgkmcnt(0)
	v_pk_fma_f32 v[160:161], v[144:145], v[126:127], v[168:169]
	v_lshl_add_u64 v[158:159], s[8:9], 0, v[158:159]
	v_lshl_add_u64 v[170:171], v[158:159], 0, v[170:171]
	v_pk_fma_f32 v[158:159], v[142:143], v[124:125], v[166:167]
	global_store_dwordx4 v[170:171], v[158:161], off
	s_mov_b64 s[8:9], 0
	s_waitcnt lgkmcnt(0)
	v_pk_fma_f32 v[160:161], v[140:141], v[122:123], v[178:179]
	v_pk_fma_f32 v[158:159], v[138:139], v[120:121], v[176:177]
	global_store_dwordx4 v[170:171], v[158:161], off offset:64
	s_waitcnt lgkmcnt(0)
	s_nop 0
	v_pk_fma_f32 v[160:161], v[136:137], v[118:119], v[182:183]
	v_pk_fma_f32 v[158:159], v[134:135], v[116:117], v[180:181]
	global_store_dwordx4 v[170:171], v[158:161], off offset:512
	s_waitcnt lgkmcnt(0)
	s_nop 0
	v_pk_fma_f32 v[160:161], v[132:133], v[114:115], v[186:187]
	v_pk_fma_f32 v[158:159], v[130:131], v[112:113], v[184:185]
	global_store_dwordx4 v[170:171], v[158:161], off offset:576

.LBB0_846:
	s_or_b64 exec, exec, s[8:9]
	v_add_u32_e32 v134, s3, v165
	v_ashrrev_i32_e32 v135, 31, v134
	v_lshlrev_b64 v[136:137], 2, v[134:135]
	v_lshl_add_u64 v[138:139], v[132:133], 0, v[136:137]
	global_load_dwordx4 v[132:135], v[138:139], off
	global_load_dwordx4 v[176:179], v[138:139], off offset:64
	global_load_dwordx4 v[180:183], v[138:139], off offset:512
	global_load_dwordx4 v[184:187], v[138:139], off offset:576
	v_readlane_b32 s8, v255, 10
	v_readlane_b32 s9, v255, 11
	s_waitcnt vmcnt(0) lgkmcnt(0)
	v_pk_fma_f32 v[134:135], v[110:111], v[126:127], v[134:135]
	v_lshl_add_u64 v[130:131], s[8:9], 0, v[130:131]
	v_lshl_add_u64 v[136:137], v[130:131], 0, v[136:137]
	v_pk_fma_f32 v[132:133], v[108:109], v[124:125], v[132:133]
	global_store_dwordx4 v[136:137], v[132:135], off
	s_waitcnt lgkmcnt(0)
	s_nop 0
	v_pk_fma_f32 v[132:133], v[106:107], v[122:123], v[178:179]
	v_pk_fma_f32 v[130:131], v[104:105], v[120:121], v[176:177]
	global_store_dwordx4 v[136:137], v[130:133], off offset:64
	s_waitcnt lgkmcnt(0)
	s_nop 0
	v_pk_fma_f32 v[132:133], v[102:103], v[118:119], v[182:183]
	v_pk_fma_f32 v[130:131], v[100:101], v[116:117], v[180:181]
	global_store_dwordx4 v[136:137], v[130:133], off offset:512
	s_waitcnt lgkmcnt(0)
	s_nop 0
	v_pk_fma_f32 v[132:133], v[98:99], v[114:115], v[186:187]
	v_pk_fma_f32 v[130:131], v[96:97], v[112:113], v[184:185]
	global_store_dwordx4 v[136:137], v[130:133], off offset:576

.LBB0_852:
	s_or_b64 exec, exec, s[8:9]
	v_add_u32_e32 v100, s3, v165
	v_ashrrev_i32_e32 v101, 31, v100
	v_lshlrev_b64 v[102:103], 2, v[100:101]
	v_lshl_add_u64 v[104:105], v[98:99], 0, v[102:103]
	global_load_dwordx4 v[98:101], v[104:105], off
	global_load_dwordx4 v[176:179], v[104:105], off offset:64
	global_load_dwordx4 v[180:183], v[104:105], off offset:512
	global_load_dwordx4 v[184:187], v[104:105], off offset:576
	v_readlane_b32 s8, v255, 10
	v_readlane_b32 s9, v255, 11
	s_waitcnt vmcnt(0) lgkmcnt(0)
	v_pk_fma_f32 v[100:101], v[94:95], v[126:127], v[100:101]
	v_lshl_add_u64 v[96:97], s[8:9], 0, v[96:97]
	v_lshl_add_u64 v[102:103], v[96:97], 0, v[102:103]
	v_pk_fma_f32 v[98:99], v[92:93], v[124:125], v[98:99]
	global_store_dwordx4 v[102:103], v[98:101], off
	s_waitcnt lgkmcnt(0)
	s_nop 0
	v_pk_fma_f32 v[98:99], v[90:91], v[122:123], v[178:179]
	v_pk_fma_f32 v[96:97], v[88:89], v[120:121], v[176:177]
	global_store_dwordx4 v[102:103], v[96:99], off offset:64
	s_waitcnt lgkmcnt(0)
	s_nop 0
	v_pk_fma_f32 v[98:99], v[86:87], v[118:119], v[182:183]
	v_pk_fma_f32 v[96:97], v[84:85], v[116:117], v[180:181]
	global_store_dwordx4 v[102:103], v[96:99], off offset:512
	s_waitcnt lgkmcnt(0)
	s_nop 0
	v_pk_fma_f32 v[98:99], v[82:83], v[114:115], v[186:187]
	v_pk_fma_f32 v[96:97], v[80:81], v[112:113], v[184:185]
	global_store_dwordx4 v[102:103], v[96:99], off offset:576

.LBB0_858:
	s_or_b64 exec, exec, s[8:9]
	v_add_u32_e32 v84, s3, v165
	v_ashrrev_i32_e32 v85, 31, v84
	v_lshlrev_b64 v[86:87], 2, v[84:85]
	v_lshl_add_u64 v[88:89], v[82:83], 0, v[86:87]
	global_load_dwordx4 v[82:85], v[88:89], off
	global_load_dwordx4 v[176:179], v[88:89], off offset:64
	global_load_dwordx4 v[180:183], v[88:89], off offset:512
	global_load_dwordx4 v[184:187], v[88:89], off offset:576
	v_readlane_b32 s8, v255, 10
	v_readlane_b32 s9, v255, 11
	s_waitcnt vmcnt(0) lgkmcnt(0)
	v_pk_fma_f32 v[84:85], v[78:79], v[126:127], v[84:85]
	v_lshl_add_u64 v[80:81], s[8:9], 0, v[80:81]
	v_lshl_add_u64 v[86:87], v[80:81], 0, v[86:87]
	v_pk_fma_f32 v[82:83], v[76:77], v[124:125], v[82:83]
	global_store_dwordx4 v[86:87], v[82:85], off
	s_waitcnt lgkmcnt(0)
	s_nop 0
	v_pk_fma_f32 v[82:83], v[74:75], v[122:123], v[178:179]
	v_pk_fma_f32 v[80:81], v[72:73], v[120:121], v[176:177]
	global_store_dwordx4 v[86:87], v[80:83], off offset:64
	s_waitcnt lgkmcnt(0)
	s_nop 0
	v_pk_fma_f32 v[82:83], v[70:71], v[118:119], v[182:183]
	v_pk_fma_f32 v[80:81], v[68:69], v[116:117], v[180:181]
	global_store_dwordx4 v[86:87], v[80:83], off offset:512
	s_waitcnt lgkmcnt(0)
	s_nop 0
	v_pk_fma_f32 v[82:83], v[66:67], v[114:115], v[186:187]
	v_pk_fma_f32 v[80:81], v[64:65], v[112:113], v[184:185]
	global_store_dwordx4 v[86:87], v[80:83], off offset:576

.LBB0_864:
	s_or_b64 exec, exec, s[8:9]
	v_add_u32_e32 v68, s3, v165
	v_ashrrev_i32_e32 v69, 31, v68
	v_lshlrev_b64 v[70:71], 2, v[68:69]
	v_lshl_add_u64 v[72:73], v[66:67], 0, v[70:71]
	global_load_dwordx4 v[66:69], v[72:73], off
	global_load_dwordx4 v[176:179], v[72:73], off offset:64
	global_load_dwordx4 v[180:183], v[72:73], off offset:512
	global_load_dwordx4 v[184:187], v[72:73], off offset:576
	v_readlane_b32 s8, v255, 10
	v_readlane_b32 s9, v255, 11
	s_waitcnt vmcnt(0) lgkmcnt(0)
	v_pk_fma_f32 v[68:69], v[62:63], v[126:127], v[68:69]
	v_lshl_add_u64 v[64:65], s[8:9], 0, v[64:65]
	v_lshl_add_u64 v[70:71], v[64:65], 0, v[70:71]
	v_pk_fma_f32 v[66:67], v[60:61], v[124:125], v[66:67]
	global_store_dwordx4 v[70:71], v[66:69], off
	s_waitcnt lgkmcnt(0)
	s_nop 0
	v_pk_fma_f32 v[66:67], v[58:59], v[122:123], v[178:179]
	v_pk_fma_f32 v[64:65], v[56:57], v[120:121], v[176:177]
	global_store_dwordx4 v[70:71], v[64:67], off offset:64
	s_waitcnt lgkmcnt(0)
	s_nop 0
	v_pk_fma_f32 v[66:67], v[54:55], v[118:119], v[182:183]
	v_pk_fma_f32 v[64:65], v[52:53], v[116:117], v[180:181]
	global_store_dwordx4 v[70:71], v[64:67], off offset:512
	s_waitcnt lgkmcnt(0)
	s_nop 0
	v_pk_fma_f32 v[66:67], v[50:51], v[114:115], v[186:187]
	v_pk_fma_f32 v[64:65], v[48:49], v[112:113], v[184:185]
	global_store_dwordx4 v[70:71], v[64:67], off offset:576

.LBB0_870:
	s_or_b64 exec, exec, s[8:9]
	v_add_u32_e32 v52, s3, v165
	v_ashrrev_i32_e32 v53, 31, v52
	v_lshlrev_b64 v[54:55], 2, v[52:53]
	v_lshl_add_u64 v[56:57], v[50:51], 0, v[54:55]
	global_load_dwordx4 v[50:53], v[56:57], off
	global_load_dwordx4 v[176:179], v[56:57], off offset:64
	global_load_dwordx4 v[180:183], v[56:57], off offset:512
	global_load_dwordx4 v[184:187], v[56:57], off offset:576
	v_readlane_b32 s8, v255, 10
	v_readlane_b32 s9, v255, 11
	s_waitcnt vmcnt(0) lgkmcnt(0)
	v_pk_fma_f32 v[52:53], v[46:47], v[126:127], v[52:53]
	v_lshl_add_u64 v[48:49], s[8:9], 0, v[48:49]
	v_lshl_add_u64 v[54:55], v[48:49], 0, v[54:55]
	v_pk_fma_f32 v[50:51], v[44:45], v[124:125], v[50:51]
	global_store_dwordx4 v[54:55], v[50:53], off
	s_waitcnt lgkmcnt(0)
	s_nop 0
	v_pk_fma_f32 v[50:51], v[42:43], v[122:123], v[178:179]
	v_pk_fma_f32 v[48:49], v[40:41], v[120:121], v[176:177]
	global_store_dwordx4 v[54:55], v[48:51], off offset:64
	s_waitcnt lgkmcnt(0)
	s_nop 0
	v_pk_fma_f32 v[50:51], v[38:39], v[118:119], v[182:183]
	v_pk_fma_f32 v[48:49], v[36:37], v[116:117], v[180:181]
	global_store_dwordx4 v[54:55], v[48:51], off offset:512
	s_waitcnt lgkmcnt(0)
	s_nop 0
	v_pk_fma_f32 v[50:51], v[34:35], v[114:115], v[186:187]
	v_pk_fma_f32 v[48:49], v[32:33], v[112:113], v[184:185]
	global_store_dwordx4 v[54:55], v[48:51], off offset:576

.LBB0_876:
	s_or_b64 exec, exec, s[8:9]
	v_add_u32_e32 v36, s3, v165
	v_ashrrev_i32_e32 v37, 31, v36
	v_lshlrev_b64 v[38:39], 2, v[36:37]
	v_lshl_add_u64 v[40:41], v[34:35], 0, v[38:39]
	global_load_dwordx4 v[34:37], v[40:41], off
	global_load_dwordx4 v[176:179], v[40:41], off offset:64
	global_load_dwordx4 v[180:183], v[40:41], off offset:512
	global_load_dwordx4 v[184:187], v[40:41], off offset:576
	v_readlane_b32 s8, v255, 10
	v_readlane_b32 s9, v255, 11
	s_waitcnt vmcnt(0) lgkmcnt(0)
	v_pk_fma_f32 v[36:37], v[30:31], v[126:127], v[36:37]
	v_lshl_add_u64 v[32:33], s[8:9], 0, v[32:33]
	v_lshl_add_u64 v[38:39], v[32:33], 0, v[38:39]
	v_pk_fma_f32 v[34:35], v[28:29], v[124:125], v[34:35]
	global_store_dwordx4 v[38:39], v[34:37], off
	s_waitcnt lgkmcnt(0)
	s_nop 0
	v_pk_fma_f32 v[34:35], v[26:27], v[122:123], v[178:179]
	v_pk_fma_f32 v[32:33], v[24:25], v[120:121], v[176:177]
	global_store_dwordx4 v[38:39], v[32:35], off offset:64
	s_waitcnt lgkmcnt(0)
	s_nop 0
	v_pk_fma_f32 v[34:35], v[22:23], v[118:119], v[182:183]
	v_pk_fma_f32 v[32:33], v[20:21], v[116:117], v[180:181]
	global_store_dwordx4 v[38:39], v[32:35], off offset:512
	s_waitcnt lgkmcnt(0)
	s_nop 0
	v_pk_fma_f32 v[34:35], v[18:19], v[114:115], v[186:187]
	v_pk_fma_f32 v[32:33], v[16:17], v[112:113], v[184:185]
	global_store_dwordx4 v[38:39], v[32:35], off offset:576

.LBB0_882:
	s_or_b64 exec, exec, s[8:9]
	v_add_u32_e32 v20, s3, v165
	v_ashrrev_i32_e32 v21, 31, v20
	v_lshlrev_b64 v[22:23], 2, v[20:21]
	v_lshl_add_u64 v[24:25], v[18:19], 0, v[22:23]
	global_load_dwordx4 v[18:21], v[24:25], off
	global_load_dwordx4 v[176:179], v[24:25], off offset:64
	global_load_dwordx4 v[180:183], v[24:25], off offset:512
	global_load_dwordx4 v[184:187], v[24:25], off offset:576
	v_readlane_b32 s8, v255, 10
	v_readlane_b32 s9, v255, 11
	s_waitcnt vmcnt(0) lgkmcnt(0)
	v_pk_fma_f32 v[20:21], v[14:15], v[126:127], v[20:21]
	v_lshl_add_u64 v[16:17], s[8:9], 0, v[16:17]
	v_lshl_add_u64 v[22:23], v[16:17], 0, v[22:23]
	v_pk_fma_f32 v[18:19], v[12:13], v[124:125], v[18:19]
	global_store_dwordx4 v[22:23], v[18:21], off
	s_waitcnt lgkmcnt(0)
	s_nop 0
	v_pk_fma_f32 v[18:19], v[10:11], v[122:123], v[178:179]
	v_pk_fma_f32 v[16:17], v[8:9], v[120:121], v[176:177]
	global_store_dwordx4 v[22:23], v[16:19], off offset:64
	s_waitcnt lgkmcnt(0)
	s_nop 0
	v_pk_fma_f32 v[18:19], v[6:7], v[118:119], v[182:183]
	v_pk_fma_f32 v[16:17], v[4:5], v[116:117], v[180:181]
	global_store_dwordx4 v[22:23], v[16:19], off offset:512
	s_waitcnt lgkmcnt(0)
	s_nop 0
	v_pk_fma_f32 v[18:19], v[2:3], v[114:115], v[186:187]
	v_pk_fma_f32 v[16:17], v[0:1], v[112:113], v[184:185]
	global_store_dwordx4 v[22:23], v[16:19], off offset:576

.LBB0_923:
	s_or_b64 exec, exec, s[8:9]
	v_add_u32_e32 v154, s0, v154
	v_ashrrev_i32_e32 v155, 31, v154
	v_lshlrev_b64 v[154:155], 2, v[154:155]
	v_lshl_add_u64 v[160:161], v[160:161], 0, v[154:155]
	global_load_dwordx4 v[166:169], v[160:161], off
	global_load_dwordx4 v[172:175], v[160:161], off offset:64
	global_load_dwordx4 v[176:179], v[160:161], off offset:512
	global_load_dwordx4 v[180:183], v[160:161], off offset:576
	v_readlane_b32 s0, v255, 10
	v_readlane_b32 s1, v255, 11
	s_waitcnt vmcnt(0) lgkmcnt(0)
	v_pk_fma_f32 v[126:127], v[126:127], v[144:145], v[168:169]
	v_lshl_add_u64 v[158:159], s[0:1], 0, v[158:159]
	v_lshl_add_u64 v[158:159], v[158:159], 0, v[154:155]
	v_pk_fma_f32 v[124:125], v[124:125], v[142:143], v[166:167]
	global_store_dwordx4 v[158:159], v[124:127], off
	s_movk_i32 s0, 0x3fff
	s_waitcnt lgkmcnt(0)
	v_pk_fma_f32 v[122:123], v[122:123], v[140:141], v[174:175]
	v_pk_fma_f32 v[120:121], v[120:121], v[138:139], v[172:173]
	global_store_dwordx4 v[158:159], v[120:123], off offset:64
	s_waitcnt lgkmcnt(0)
	v_pk_fma_f32 v[118:119], v[118:119], v[136:137], v[178:179]
	v_pk_fma_f32 v[116:117], v[116:117], v[134:135], v[176:177]
	global_store_dwordx4 v[158:159], v[116:119], off offset:512
	s_waitcnt lgkmcnt(0)
	v_pk_fma_f32 v[114:115], v[114:115], v[132:133], v[182:183]
	v_add_u32_e32 v116, 16, v156
	v_pk_fma_f32 v[112:113], v[112:113], v[130:131], v[180:181]
	v_cmp_lt_i32_e32 vcc, s0, v116
	global_store_dwordx4 v[158:159], v[112:115], off offset:576
	s_and_saveexec_b64 s[0:1], vcc
	s_xor_b64 s[0:1], exec, s[0:1]
	s_cbranch_execz .LBB0_925
	v_add_u32_e32 v112, 0xffffc010, v156
	v_mov_b32_e32 v113, v129
	v_readlane_b32 s8, v255, 16
	v_lshlrev_b64 v[112:113], 12, v[112:113]
	v_readlane_b32 s9, v255, 17
	v_mov_b32_e32 v117, v129
	s_nop 0
	v_lshl_add_u64 v[114:115], s[8:9], 0, v[112:113]
	v_lshlrev_b64 v[112:113], 12, v[116:117]

.LBB0_927:
	s_or_b64 exec, exec, s[0:1]
	v_lshl_add_u64 v[118:119], v[114:115], 0, v[154:155]
	global_load_dwordx4 v[114:117], v[118:119], off
	global_load_dwordx4 v[172:175], v[118:119], off offset:64
	global_load_dwordx4 v[176:179], v[118:119], off offset:512
	global_load_dwordx4 v[180:183], v[118:119], off offset:576
	v_readlane_b32 s0, v255, 10
	v_readlane_b32 s1, v255, 11
	s_waitcnt vmcnt(0) lgkmcnt(0)
	v_pk_fma_f32 v[108:109], v[108:109], v[142:143], v[114:115]
	v_lshl_add_u64 v[112:113], s[0:1], 0, v[112:113]
	v_lshl_add_u64 v[112:113], v[112:113], 0, v[154:155]
	v_pk_fma_f32 v[110:111], v[110:111], v[144:145], v[116:117]
	global_store_dwordx4 v[112:113], v[108:111], off
	s_movk_i32 s0, 0x3fff
	s_waitcnt lgkmcnt(0)
	v_pk_fma_f32 v[104:105], v[104:105], v[138:139], v[172:173]
	v_pk_fma_f32 v[106:107], v[106:107], v[140:141], v[174:175]
	global_store_dwordx4 v[112:113], v[104:107], off offset:64
	s_waitcnt lgkmcnt(0)
	v_pk_fma_f32 v[100:101], v[100:101], v[134:135], v[176:177]
	v_pk_fma_f32 v[102:103], v[102:103], v[136:137], v[178:179]
	global_store_dwordx4 v[112:113], v[100:103], off offset:512
	s_waitcnt lgkmcnt(0)
	v_pk_fma_f32 v[96:97], v[96:97], v[130:131], v[180:181]
	v_add_u32_e32 v100, 32, v156
	v_pk_fma_f32 v[98:99], v[98:99], v[132:133], v[182:183]
	v_cmp_lt_i32_e32 vcc, s0, v100
	global_store_dwordx4 v[112:113], v[96:99], off offset:576
	s_and_saveexec_b64 s[0:1], vcc
	s_xor_b64 s[0:1], exec, s[0:1]
	s_cbranch_execz .LBB0_929
	v_add_u32_e32 v96, 0xffffc020, v156
	v_mov_b32_e32 v97, v129
	v_readlane_b32 s8, v255, 16
	v_lshlrev_b64 v[96:97], 12, v[96:97]
	v_readlane_b32 s9, v255, 17
	v_mov_b32_e32 v101, v129
	s_nop 0
	v_lshl_add_u64 v[98:99], s[8:9], 0, v[96:97]
	v_lshlrev_b64 v[96:97], 12, v[100:101]

.LBB0_931:
	s_or_b64 exec, exec, s[0:1]
	v_lshl_add_u64 v[102:103], v[98:99], 0, v[154:155]
	global_load_dwordx4 v[98:101], v[102:103], off
	global_load_dwordx4 v[172:175], v[102:103], off offset:64
	global_load_dwordx4 v[176:179], v[102:103], off offset:512
	global_load_dwordx4 v[180:183], v[102:103], off offset:576
	v_readlane_b32 s0, v255, 10
	v_readlane_b32 s1, v255, 11
	s_waitcnt vmcnt(0) lgkmcnt(0)
	v_pk_fma_f32 v[92:93], v[92:93], v[142:143], v[98:99]
	v_lshl_add_u64 v[96:97], s[0:1], 0, v[96:97]
	v_lshl_add_u64 v[96:97], v[96:97], 0, v[154:155]
	v_pk_fma_f32 v[94:95], v[94:95], v[144:145], v[100:101]
	global_store_dwordx4 v[96:97], v[92:95], off
	s_movk_i32 s0, 0x3fff
	s_waitcnt lgkmcnt(0)
	v_pk_fma_f32 v[88:89], v[88:89], v[138:139], v[172:173]
	v_pk_fma_f32 v[90:91], v[90:91], v[140:141], v[174:175]
	global_store_dwordx4 v[96:97], v[88:91], off offset:64
	s_waitcnt lgkmcnt(0)
	v_pk_fma_f32 v[84:85], v[84:85], v[134:135], v[176:177]
	v_pk_fma_f32 v[86:87], v[86:87], v[136:137], v[178:179]
	global_store_dwordx4 v[96:97], v[84:87], off offset:512
	s_waitcnt lgkmcnt(0)
	v_pk_fma_f32 v[80:81], v[80:81], v[130:131], v[180:181]
	v_add_u32_e32 v84, 48, v156
	v_pk_fma_f32 v[82:83], v[82:83], v[132:133], v[182:183]
	v_cmp_lt_i32_e32 vcc, s0, v84
	global_store_dwordx4 v[96:97], v[80:83], off offset:576
	s_and_saveexec_b64 s[0:1], vcc
	s_xor_b64 s[0:1], exec, s[0:1]
	s_cbranch_execz .LBB0_933
	v_add_u32_e32 v80, 0xffffc030, v156
	v_mov_b32_e32 v81, v129
	v_readlane_b32 s8, v255, 16
	v_lshlrev_b64 v[80:81], 12, v[80:81]
	v_readlane_b32 s9, v255, 17
	v_mov_b32_e32 v85, v129
	s_nop 0
	v_lshl_add_u64 v[82:83], s[8:9], 0, v[80:81]
	v_lshlrev_b64 v[80:81], 12, v[84:85]

.LBB0_935:
	s_or_b64 exec, exec, s[0:1]
	v_lshl_add_u64 v[86:87], v[82:83], 0, v[154:155]
	global_load_dwordx4 v[82:85], v[86:87], off
	global_load_dwordx4 v[172:175], v[86:87], off offset:64
	global_load_dwordx4 v[176:179], v[86:87], off offset:512
	global_load_dwordx4 v[180:183], v[86:87], off offset:576
	v_readlane_b32 s0, v255, 10
	v_readlane_b32 s1, v255, 11
	s_waitcnt vmcnt(0) lgkmcnt(0)
	v_pk_fma_f32 v[76:77], v[76:77], v[142:143], v[82:83]
	v_lshl_add_u64 v[80:81], s[0:1], 0, v[80:81]
	v_lshl_add_u64 v[80:81], v[80:81], 0, v[154:155]
	v_pk_fma_f32 v[78:79], v[78:79], v[144:145], v[84:85]
	global_store_dwordx4 v[80:81], v[76:79], off
	s_movk_i32 s0, 0x3fff
	s_waitcnt lgkmcnt(0)
	v_pk_fma_f32 v[72:73], v[72:73], v[138:139], v[172:173]
	v_pk_fma_f32 v[74:75], v[74:75], v[140:141], v[174:175]
	global_store_dwordx4 v[80:81], v[72:75], off offset:64
	s_waitcnt lgkmcnt(0)
	v_pk_fma_f32 v[68:69], v[68:69], v[134:135], v[176:177]
	v_pk_fma_f32 v[70:71], v[70:71], v[136:137], v[178:179]
	global_store_dwordx4 v[80:81], v[68:71], off offset:512
	s_waitcnt lgkmcnt(0)
	v_pk_fma_f32 v[64:65], v[64:65], v[130:131], v[180:181]
	v_add_u32_e32 v68, 0x80, v156
	v_pk_fma_f32 v[66:67], v[66:67], v[132:133], v[182:183]
	v_cmp_lt_i32_e32 vcc, s0, v68
	global_store_dwordx4 v[80:81], v[64:67], off offset:576
	s_and_saveexec_b64 s[0:1], vcc
	s_xor_b64 s[0:1], exec, s[0:1]
	s_cbranch_execz .LBB0_937
	v_add_u32_e32 v64, 0xffffc080, v156
	v_mov_b32_e32 v65, v129
	v_readlane_b32 s8, v255, 16
	v_lshlrev_b64 v[64:65], 12, v[64:65]
	v_readlane_b32 s9, v255, 17
	v_mov_b32_e32 v69, v129
	s_nop 0
	v_lshl_add_u64 v[66:67], s[8:9], 0, v[64:65]
	v_lshlrev_b64 v[64:65], 12, v[68:69]

.LBB0_939:
	s_or_b64 exec, exec, s[0:1]
	v_lshl_add_u64 v[70:71], v[66:67], 0, v[154:155]
	global_load_dwordx4 v[66:69], v[70:71], off
	global_load_dwordx4 v[172:175], v[70:71], off offset:64
	global_load_dwordx4 v[176:179], v[70:71], off offset:512
	global_load_dwordx4 v[180:183], v[70:71], off offset:576
	v_readlane_b32 s0, v255, 10
	v_readlane_b32 s1, v255, 11
	s_waitcnt vmcnt(0) lgkmcnt(0)
	v_pk_fma_f32 v[60:61], v[60:61], v[142:143], v[66:67]
	v_lshl_add_u64 v[64:65], s[0:1], 0, v[64:65]
	v_lshl_add_u64 v[64:65], v[64:65], 0, v[154:155]
	v_pk_fma_f32 v[62:63], v[62:63], v[144:145], v[68:69]
	global_store_dwordx4 v[64:65], v[60:63], off
	s_movk_i32 s0, 0x3fff
	s_waitcnt lgkmcnt(0)
	v_pk_fma_f32 v[56:57], v[56:57], v[138:139], v[172:173]
	v_pk_fma_f32 v[58:59], v[58:59], v[140:141], v[174:175]
	global_store_dwordx4 v[64:65], v[56:59], off offset:64
	s_waitcnt lgkmcnt(0)
	v_pk_fma_f32 v[52:53], v[52:53], v[134:135], v[176:177]
	v_pk_fma_f32 v[54:55], v[54:55], v[136:137], v[178:179]
	global_store_dwordx4 v[64:65], v[52:55], off offset:512
	s_waitcnt lgkmcnt(0)
	v_pk_fma_f32 v[48:49], v[48:49], v[130:131], v[180:181]
	v_add_u32_e32 v52, 0x90, v156
	v_pk_fma_f32 v[50:51], v[50:51], v[132:133], v[182:183]
	v_cmp_lt_i32_e32 vcc, s0, v52
	global_store_dwordx4 v[64:65], v[48:51], off offset:576
	s_and_saveexec_b64 s[0:1], vcc
	s_xor_b64 s[0:1], exec, s[0:1]
	s_cbranch_execz .LBB0_941
	v_add_u32_e32 v48, 0xffffc090, v156
	v_mov_b32_e32 v49, v129
	v_readlane_b32 s8, v255, 16
	v_lshlrev_b64 v[48:49], 12, v[48:49]
	v_readlane_b32 s9, v255, 17
	v_mov_b32_e32 v53, v129
	s_nop 0
	v_lshl_add_u64 v[50:51], s[8:9], 0, v[48:49]
	v_lshlrev_b64 v[48:49], 12, v[52:53]

.LBB0_943:
	s_or_b64 exec, exec, s[0:1]
	v_lshl_add_u64 v[54:55], v[50:51], 0, v[154:155]
	global_load_dwordx4 v[50:53], v[54:55], off
	global_load_dwordx4 v[172:175], v[54:55], off offset:64
	global_load_dwordx4 v[176:179], v[54:55], off offset:512
	global_load_dwordx4 v[180:183], v[54:55], off offset:576
	v_readlane_b32 s0, v255, 10
	v_readlane_b32 s1, v255, 11
	s_waitcnt vmcnt(0) lgkmcnt(0)
	v_pk_fma_f32 v[44:45], v[44:45], v[142:143], v[50:51]
	v_lshl_add_u64 v[48:49], s[0:1], 0, v[48:49]
	v_lshl_add_u64 v[48:49], v[48:49], 0, v[154:155]
	v_pk_fma_f32 v[46:47], v[46:47], v[144:145], v[52:53]
	global_store_dwordx4 v[48:49], v[44:47], off
	s_movk_i32 s0, 0x3fff
	s_waitcnt lgkmcnt(0)
	v_pk_fma_f32 v[40:41], v[40:41], v[138:139], v[172:173]
	v_pk_fma_f32 v[42:43], v[42:43], v[140:141], v[174:175]
	global_store_dwordx4 v[48:49], v[40:43], off offset:64
	s_waitcnt lgkmcnt(0)
	v_pk_fma_f32 v[36:37], v[36:37], v[134:135], v[176:177]
	v_pk_fma_f32 v[38:39], v[38:39], v[136:137], v[178:179]
	global_store_dwordx4 v[48:49], v[36:39], off offset:512
	s_waitcnt lgkmcnt(0)
	v_pk_fma_f32 v[32:33], v[32:33], v[130:131], v[180:181]
	v_add_u32_e32 v36, 0xa0, v156
	v_pk_fma_f32 v[34:35], v[34:35], v[132:133], v[182:183]
	v_cmp_lt_i32_e32 vcc, s0, v36
	global_store_dwordx4 v[48:49], v[32:35], off offset:576
	s_and_saveexec_b64 s[0:1], vcc
	s_xor_b64 s[0:1], exec, s[0:1]
	s_cbranch_execz .LBB0_945
	v_add_u32_e32 v32, 0xffffc0a0, v156
	v_mov_b32_e32 v33, v129
	v_readlane_b32 s8, v255, 16
	v_lshlrev_b64 v[32:33], 12, v[32:33]
	v_readlane_b32 s9, v255, 17
	v_mov_b32_e32 v37, v129
	s_nop 0
	v_lshl_add_u64 v[34:35], s[8:9], 0, v[32:33]
	v_lshlrev_b64 v[32:33], 12, v[36:37]

.LBB0_947:
	s_or_b64 exec, exec, s[0:1]
	v_lshl_add_u64 v[38:39], v[34:35], 0, v[154:155]
	global_load_dwordx4 v[34:37], v[38:39], off
	global_load_dwordx4 v[172:175], v[38:39], off offset:64
	global_load_dwordx4 v[176:179], v[38:39], off offset:512
	global_load_dwordx4 v[180:183], v[38:39], off offset:576
	v_readlane_b32 s0, v255, 10
	v_readlane_b32 s1, v255, 11
	s_waitcnt vmcnt(0) lgkmcnt(0)
	v_pk_fma_f32 v[28:29], v[28:29], v[142:143], v[34:35]
	v_lshl_add_u64 v[32:33], s[0:1], 0, v[32:33]
	v_lshl_add_u64 v[32:33], v[32:33], 0, v[154:155]
	v_pk_fma_f32 v[30:31], v[30:31], v[144:145], v[36:37]
	global_store_dwordx4 v[32:33], v[28:31], off
	s_movk_i32 s0, 0x3fff
	s_waitcnt lgkmcnt(0)
	v_pk_fma_f32 v[24:25], v[24:25], v[138:139], v[172:173]
	v_pk_fma_f32 v[26:27], v[26:27], v[140:141], v[174:175]
	global_store_dwordx4 v[32:33], v[24:27], off offset:64
	s_waitcnt lgkmcnt(0)
	v_pk_fma_f32 v[20:21], v[20:21], v[134:135], v[176:177]
	v_pk_fma_f32 v[22:23], v[22:23], v[136:137], v[178:179]
	global_store_dwordx4 v[32:33], v[20:23], off offset:512
	s_waitcnt lgkmcnt(0)
	v_pk_fma_f32 v[16:17], v[16:17], v[130:131], v[180:181]
	v_add_u32_e32 v20, 0xb0, v156
	v_pk_fma_f32 v[18:19], v[18:19], v[132:133], v[182:183]
	v_cmp_lt_i32_e32 vcc, s0, v20
	global_store_dwordx4 v[32:33], v[16:19], off offset:576
	s_and_saveexec_b64 s[0:1], vcc
	s_xor_b64 s[0:1], exec, s[0:1]
	s_cbranch_execz .LBB0_949
	v_add_u32_e32 v16, 0xffffc0b0, v156
	v_mov_b32_e32 v17, v129
	v_readlane_b32 s8, v255, 16
	v_lshlrev_b64 v[16:17], 12, v[16:17]
	v_readlane_b32 s9, v255, 17
	v_mov_b32_e32 v21, v129
	s_nop 0
	v_lshl_add_u64 v[18:19], s[8:9], 0, v[16:17]
	v_lshlrev_b64 v[16:17], 12, v[20:21]

.LBB0_1968:
	s_lshl_b32 s0, s21, 8
	v_mov_b32_e32 v138, v128
	v_mov_b32_e32 v139, v144
	s_add_i32 s0, s0, s59
	v_mul_f32_e32 v124, 0xbfb8aa3b, v124
	v_add_u32_e32 v140, s0, v138
	s_lshl_b32 s0, s20, 8
	s_or_b32 s0, s0, s60
	v_lshl_add_u32 v138, v139, 2, s0
	v_ashrrev_i32_e32 v141, 31, v140
	v_lshlrev_b64 v[142:143], 10, v[140:141]
	v_ashrrev_i32_e32 v139, 31, v138
	v_lshl_add_u64 v[142:143], s[44:45], 0, v[142:143]
	v_lshlrev_b64 v[138:139], 1, v[138:139]
	v_lshl_add_u64 v[142:143], v[142:143], 0, v[138:139]
	global_load_dwordx2 v[150:151], v[142:143], off
	global_load_dwordx2 v[156:157], v[142:143], off offset:32
	global_load_dwordx2 v[158:159], v[142:143], off offset:256
	global_load_dwordx2 v[160:161], v[142:143], off offset:288
	v_mul_f32_e32 v125, 0xbfb8aa3b, v125
	v_exp_f32_e32 v124, v124
	v_exp_f32_e32 v125, v125
	v_lshlrev_b64 v[148:149], 11, v[140:141]
	v_mul_f32_e32 v126, 0xbfb8aa3b, v126
	v_mul_f32_e32 v127, 0xbfb8aa3b, v127
	v_pk_add_f32 v[124:125], v[124:125], 1.0 op_sel_hi:[1,0]
	v_exp_f32_e32 v126, v126
	v_div_scale_f32 v141, s[0:1], v125, v125, 1.0
	v_rcp_f32_e32 v147, v141
	v_exp_f32_e32 v127, v127
	v_mul_f32_e32 v120, 0xbfb8aa3b, v120
	v_mul_f32_e32 v121, 0xbfb8aa3b, v121
	v_exp_f32_e32 v120, v120
	v_pk_add_f32 v[126:127], v[126:127], 1.0 op_sel_hi:[1,0]
	v_exp_f32_e32 v121, v121
	v_readlane_b32 s2, v251, 3
	v_readlane_b32 s3, v251, 4
	v_mul_f32_e32 v122, 0xbfb8aa3b, v122
	v_pk_add_f32 v[120:121], v[120:121], 1.0 op_sel_hi:[1,0]
	v_mul_f32_e32 v123, 0xbfb8aa3b, v123
	v_exp_f32_e32 v122, v122
	v_exp_f32_e32 v123, v123
	v_mul_f32_e32 v116, 0xbfb8aa3b, v116
	v_mul_f32_e32 v117, 0xbfb8aa3b, v117
	v_exp_f32_e32 v116, v116
	v_pk_add_f32 v[122:123], v[122:123], 1.0 op_sel_hi:[1,0]
	v_exp_f32_e32 v117, v117
	v_mul_f32_e32 v118, 0xbfb8aa3b, v118
	v_mul_f32_e32 v119, 0xbfb8aa3b, v119
	v_exp_f32_e32 v118, v118
	v_pk_add_f32 v[116:117], v[116:117], 1.0 op_sel_hi:[1,0]
	v_exp_f32_e32 v119, v119
	v_mul_f32_e32 v112, 0xbfb8aa3b, v112
	v_mul_f32_e32 v113, 0xbfb8aa3b, v113
	v_exp_f32_e32 v112, v112
	v_pk_add_f32 v[118:119], v[118:119], 1.0 op_sel_hi:[1,0]
	v_exp_f32_e32 v113, v113
	v_mul_f32_e32 v114, 0xbfb8aa3b, v114
	v_mul_f32_e32 v115, 0xbfb8aa3b, v115
	v_exp_f32_e32 v114, v114
	v_pk_add_f32 v[112:113], v[112:113], 1.0 op_sel_hi:[1,0]
	v_exp_f32_e32 v115, v115
	v_mul_f32_e32 v108, 0xbfb8aa3b, v108
	v_mul_f32_e32 v109, 0xbfb8aa3b, v109
	v_exp_f32_e32 v108, v108
	v_pk_add_f32 v[114:115], v[114:115], 1.0 op_sel_hi:[1,0]
	v_exp_f32_e32 v109, v109
	v_mul_f32_e32 v110, 0xbfb8aa3b, v110
	v_mul_f32_e32 v111, 0xbfb8aa3b, v111
	v_exp_f32_e32 v110, v110
	v_pk_add_f32 v[108:109], v[108:109], 1.0 op_sel_hi:[1,0]
	v_exp_f32_e32 v111, v111
	v_mul_f32_e32 v104, 0xbfb8aa3b, v104
	v_mul_f32_e32 v105, 0xbfb8aa3b, v105
	v_exp_f32_e32 v104, v104
	v_pk_add_f32 v[110:111], v[110:111], 1.0 op_sel_hi:[1,0]
	v_exp_f32_e32 v105, v105
	v_mul_f32_e32 v106, 0xbfb8aa3b, v106
	v_mul_f32_e32 v107, 0xbfb8aa3b, v107
	v_exp_f32_e32 v106, v106
	v_pk_add_f32 v[104:105], v[104:105], 1.0 op_sel_hi:[1,0]
	v_exp_f32_e32 v107, v107
	v_mul_f32_e32 v100, 0xbfb8aa3b, v100
	v_mul_f32_e32 v101, 0xbfb8aa3b, v101
	v_exp_f32_e32 v100, v100
	v_pk_add_f32 v[106:107], v[106:107], 1.0 op_sel_hi:[1,0]
	v_exp_f32_e32 v101, v101
	v_mul_f32_e32 v102, 0xbfb8aa3b, v102
	v_mul_f32_e32 v103, 0xbfb8aa3b, v103
	v_exp_f32_e32 v102, v102
	v_pk_add_f32 v[100:101], v[100:101], 1.0 op_sel_hi:[1,0]
	v_exp_f32_e32 v103, v103
	v_mul_f32_e32 v96, 0xbfb8aa3b, v96
	v_mul_f32_e32 v97, 0xbfb8aa3b, v97
	v_exp_f32_e32 v96, v96
	v_pk_add_f32 v[102:103], v[102:103], 1.0 op_sel_hi:[1,0]
	v_exp_f32_e32 v97, v97
	s_waitcnt vmcnt(0) lgkmcnt(0)
	v_lshlrev_b32_e32 v152, 16, v150
	v_and_b32_e32 v153, 0xffff0000, v150
	v_fma_f32 v150, -v141, v147, 1.0
	v_fmac_f32_e32 v147, v150, v147
	v_div_scale_f32 v150, vcc, 1.0, v125, 1.0
	v_mul_f32_e32 v154, v150, v147
	v_fma_f32 v155, -v141, v154, v150
	v_fmac_f32_e32 v154, v155, v147
	v_fma_f32 v141, -v141, v154, v150
	v_div_fmas_f32 v141, v141, v147, v154
	v_div_fixup_f32 v125, v141, v125, 1.0
	v_rcp_f32_e32 v147, v124
	v_pk_add_f32 v[96:97], v[96:97], 1.0 op_sel_hi:[1,0]
	v_mul_f32_e32 v98, 0xbfb8aa3b, v98
	v_mul_f32_e32 v99, 0xbfb8aa3b, v99
	v_mul_f32_e32 v124, 1.0, v147
	v_rcp_f32_e32 v147, v127
	v_pk_mul_f32 v[124:125], v[124:125], v[152:153]
	v_lshlrev_b32_e32 v150, 16, v151
	v_and_b32_e32 v151, 0xffff0000, v151
	v_mul_f32_e32 v127, 1.0, v147
	v_rcp_f32_e32 v147, v126
	v_exp_f32_e32 v98, v98
	v_exp_f32_e32 v99, v99
	v_mul_f32_e32 v92, 0xbfb8aa3b, v92
	v_mul_f32_e32 v126, 1.0, v147
	v_pk_mul_f32 v[126:127], v[126:127], v[150:151]
	v_cvt_pk_bf16_f32 v150, v124, v125
	v_cvt_pk_bf16_f32 v151, v126, v127
	v_lshl_add_u64 v[124:125], s[2:3], 0, v[148:149]
	v_lshl_add_u64 v[124:125], v[124:125], 0, v[138:139]
	global_store_dwordx2 v[124:125], v[150:151], off
	v_pk_add_f32 v[98:99], v[98:99], 1.0 op_sel_hi:[1,0]
	v_mul_f32_e32 v93, 0xbfb8aa3b, v93
	v_exp_f32_e32 v92, v92
	v_exp_f32_e32 v93, v93
	v_mul_f32_e32 v94, 0xbfb8aa3b, v94
	v_mul_f32_e32 v95, 0xbfb8aa3b, v95
	v_exp_f32_e32 v94, v94
	v_pk_add_f32 v[92:93], v[92:93], 1.0 op_sel_hi:[1,0]
	v_exp_f32_e32 v95, v95
	v_mul_f32_e32 v88, 0xbfb8aa3b, v88
	v_mul_f32_e32 v89, 0xbfb8aa3b, v89
	v_exp_f32_e32 v88, v88
	v_pk_add_f32 v[94:95], v[94:95], 1.0 op_sel_hi:[1,0]
	v_exp_f32_e32 v89, v89
	v_mul_f32_e32 v90, 0xbfb8aa3b, v90
	v_mul_f32_e32 v91, 0xbfb8aa3b, v91
	v_exp_f32_e32 v90, v90
	v_pk_add_f32 v[88:89], v[88:89], 1.0 op_sel_hi:[1,0]
	v_exp_f32_e32 v91, v91
	v_mul_f32_e32 v84, 0xbfb8aa3b, v84
	v_mul_f32_e32 v85, 0xbfb8aa3b, v85
	v_exp_f32_e32 v84, v84
	v_pk_add_f32 v[90:91], v[90:91], 1.0 op_sel_hi:[1,0]
	v_exp_f32_e32 v85, v85
	v_mul_f32_e32 v86, 0xbfb8aa3b, v86
	v_mul_f32_e32 v87, 0xbfb8aa3b, v87
	v_exp_f32_e32 v86, v86
	v_pk_add_f32 v[84:85], v[84:85], 1.0 op_sel_hi:[1,0]
	v_exp_f32_e32 v87, v87
	v_mul_f32_e32 v80, 0xbfb8aa3b, v80
	v_mul_f32_e32 v81, 0xbfb8aa3b, v81
	v_exp_f32_e32 v80, v80
	v_pk_add_f32 v[86:87], v[86:87], 1.0 op_sel_hi:[1,0]
	v_exp_f32_e32 v81, v81
	v_mul_f32_e32 v82, 0xbfb8aa3b, v82
	v_mul_f32_e32 v83, 0xbfb8aa3b, v83
	v_exp_f32_e32 v82, v82
	v_pk_add_f32 v[80:81], v[80:81], 1.0 op_sel_hi:[1,0]
	v_exp_f32_e32 v83, v83
	v_mul_f32_e32 v76, 0xbfb8aa3b, v76
	v_mul_f32_e32 v77, 0xbfb8aa3b, v77
	v_exp_f32_e32 v76, v76
	v_pk_add_f32 v[82:83], v[82:83], 1.0 op_sel_hi:[1,0]
	v_exp_f32_e32 v77, v77
	v_mul_f32_e32 v78, 0xbfb8aa3b, v78
	v_mul_f32_e32 v79, 0xbfb8aa3b, v79
	v_exp_f32_e32 v78, v78
	v_pk_add_f32 v[76:77], v[76:77], 1.0 op_sel_hi:[1,0]
	v_exp_f32_e32 v79, v79
	v_mul_f32_e32 v72, 0xbfb8aa3b, v72
	v_mul_f32_e32 v73, 0xbfb8aa3b, v73
	v_exp_f32_e32 v72, v72
	v_pk_add_f32 v[78:79], v[78:79], 1.0 op_sel_hi:[1,0]
	v_exp_f32_e32 v73, v73
	v_mul_f32_e32 v74, 0xbfb8aa3b, v74
	v_mul_f32_e32 v75, 0xbfb8aa3b, v75
	v_exp_f32_e32 v74, v74
	v_pk_add_f32 v[72:73], v[72:73], 1.0 op_sel_hi:[1,0]
	v_exp_f32_e32 v75, v75
	v_mul_f32_e32 v68, 0xbfb8aa3b, v68
	v_mul_f32_e32 v69, 0xbfb8aa3b, v69
	v_exp_f32_e32 v68, v68
	v_pk_add_f32 v[74:75], v[74:75], 1.0 op_sel_hi:[1,0]
	v_exp_f32_e32 v69, v69
	v_mul_f32_e32 v70, 0xbfb8aa3b, v70
	v_mul_f32_e32 v71, 0xbfb8aa3b, v71
	v_exp_f32_e32 v70, v70
	v_pk_add_f32 v[68:69], v[68:69], 1.0 op_sel_hi:[1,0]
	v_exp_f32_e32 v71, v71
	v_mul_f32_e32 v64, 0xbfb8aa3b, v64
	v_mul_f32_e32 v65, 0xbfb8aa3b, v65
	v_exp_f32_e32 v64, v64
	v_pk_add_f32 v[70:71], v[70:71], 1.0 op_sel_hi:[1,0]
	v_exp_f32_e32 v65, v65
	v_mul_f32_e32 v66, 0xbfb8aa3b, v66
	v_mul_f32_e32 v67, 0xbfb8aa3b, v67
	s_waitcnt lgkmcnt(0)
	v_lshlrev_b32_e32 v148, 16, v156
	v_and_b32_e32 v149, 0xffff0000, v156
	v_rcp_f32_e32 v141, v121
	v_pk_add_f32 v[64:65], v[64:65], 1.0 op_sel_hi:[1,0]
	v_exp_f32_e32 v66, v66
	v_exp_f32_e32 v67, v67
	v_mul_f32_e32 v121, 1.0, v141
	v_div_scale_f32 v126, s[0:1], v120, v120, 1.0
	v_rcp_f32_e32 v141, v126
	v_pk_add_f32 v[66:67], v[66:67], 1.0 op_sel_hi:[1,0]
	v_mul_f32_e32 v60, 0xbfb8aa3b, v60
	v_mul_f32_e32 v61, 0xbfb8aa3b, v61
	v_fma_f32 v147, -v126, v141, 1.0
	v_fmac_f32_e32 v141, v147, v141
	v_div_scale_f32 v147, vcc, 1.0, v120, 1.0
	v_mul_f32_e32 v150, v147, v141
	v_fma_f32 v151, -v126, v150, v147
	v_fmac_f32_e32 v150, v151, v141
	v_fma_f32 v126, -v126, v150, v147
	v_div_fmas_f32 v126, v126, v141, v150
	v_rcp_f32_e32 v147, v123
	v_div_fixup_f32 v120, v126, v120, 1.0
	v_pk_mul_f32 v[120:121], v[120:121], v[148:149]
	v_lshlrev_b32_e32 v126, 16, v157
	v_mul_f32_e32 v123, 1.0, v147
	v_rcp_f32_e32 v147, v122
	v_and_b32_e32 v127, 0xffff0000, v157
	v_cvt_pk_bf16_f32 v120, v120, v121
	v_exp_f32_e32 v60, v60
	v_mul_f32_e32 v122, 1.0, v147
	v_pk_mul_f32 v[122:123], v[122:123], v[126:127]
	v_exp_f32_e32 v61, v61
	v_cvt_pk_bf16_f32 v121, v122, v123
	global_store_dwordx2 v[124:125], v[120:121], off offset:32
	v_pk_add_f32 v[60:61], v[60:61], 1.0 op_sel_hi:[1,0]
	v_mul_f32_e32 v62, 0xbfb8aa3b, v62
	v_mul_f32_e32 v63, 0xbfb8aa3b, v63
	v_exp_f32_e32 v62, v62
	v_exp_f32_e32 v63, v63
	v_mul_f32_e32 v56, 0xbfb8aa3b, v56
	v_mul_f32_e32 v57, 0xbfb8aa3b, v57
	v_exp_f32_e32 v56, v56
	v_pk_add_f32 v[62:63], v[62:63], 1.0 op_sel_hi:[1,0]
	v_exp_f32_e32 v57, v57
	v_mul_f32_e32 v58, 0xbfb8aa3b, v58
	v_mul_f32_e32 v59, 0xbfb8aa3b, v59
	v_exp_f32_e32 v58, v58
	v_pk_add_f32 v[56:57], v[56:57], 1.0 op_sel_hi:[1,0]
	v_exp_f32_e32 v59, v59
	v_mul_f32_e32 v52, 0xbfb8aa3b, v52
	v_mul_f32_e32 v53, 0xbfb8aa3b, v53
	v_exp_f32_e32 v52, v52
	v_pk_add_f32 v[58:59], v[58:59], 1.0 op_sel_hi:[1,0]
	v_exp_f32_e32 v53, v53
	v_mul_f32_e32 v54, 0xbfb8aa3b, v54
	v_mul_f32_e32 v55, 0xbfb8aa3b, v55
	v_exp_f32_e32 v54, v54
	v_pk_add_f32 v[52:53], v[52:53], 1.0 op_sel_hi:[1,0]
	v_exp_f32_e32 v55, v55
	v_mul_f32_e32 v48, 0xbfb8aa3b, v48
	v_mul_f32_e32 v49, 0xbfb8aa3b, v49
	v_exp_f32_e32 v48, v48
	v_pk_add_f32 v[54:55], v[54:55], 1.0 op_sel_hi:[1,0]
	v_exp_f32_e32 v49, v49
	v_mul_f32_e32 v50, 0xbfb8aa3b, v50
	v_mul_f32_e32 v51, 0xbfb8aa3b, v51
	v_exp_f32_e32 v50, v50
	v_pk_add_f32 v[48:49], v[48:49], 1.0 op_sel_hi:[1,0]
	v_exp_f32_e32 v51, v51
	v_mul_f32_e32 v44, 0xbfb8aa3b, v44
	v_mul_f32_e32 v45, 0xbfb8aa3b, v45
	v_exp_f32_e32 v44, v44
	v_pk_add_f32 v[50:51], v[50:51], 1.0 op_sel_hi:[1,0]
	v_exp_f32_e32 v45, v45
	v_mul_f32_e32 v46, 0xbfb8aa3b, v46
	v_mul_f32_e32 v47, 0xbfb8aa3b, v47
	v_exp_f32_e32 v46, v46
	v_pk_add_f32 v[44:45], v[44:45], 1.0 op_sel_hi:[1,0]
	v_exp_f32_e32 v47, v47
	v_mul_f32_e32 v40, 0xbfb8aa3b, v40
	v_mul_f32_e32 v41, 0xbfb8aa3b, v41
	v_exp_f32_e32 v40, v40
	v_pk_add_f32 v[46:47], v[46:47], 1.0 op_sel_hi:[1,0]
	v_exp_f32_e32 v41, v41
	v_mul_f32_e32 v42, 0xbfb8aa3b, v42
	v_mul_f32_e32 v43, 0xbfb8aa3b, v43
	v_exp_f32_e32 v42, v42
	v_pk_add_f32 v[40:41], v[40:41], 1.0 op_sel_hi:[1,0]
	v_exp_f32_e32 v43, v43
	v_mul_f32_e32 v36, 0xbfb8aa3b, v36
	v_mul_f32_e32 v37, 0xbfb8aa3b, v37
	v_exp_f32_e32 v36, v36
	v_pk_add_f32 v[42:43], v[42:43], 1.0 op_sel_hi:[1,0]
	v_exp_f32_e32 v37, v37
	v_mul_f32_e32 v38, 0xbfb8aa3b, v38
	v_mul_f32_e32 v39, 0xbfb8aa3b, v39
	v_exp_f32_e32 v38, v38
	v_pk_add_f32 v[36:37], v[36:37], 1.0 op_sel_hi:[1,0]
	v_exp_f32_e32 v39, v39
	v_mul_f32_e32 v32, 0xbfb8aa3b, v32
	v_mul_f32_e32 v33, 0xbfb8aa3b, v33
	v_exp_f32_e32 v32, v32
	v_pk_add_f32 v[38:39], v[38:39], 1.0 op_sel_hi:[1,0]
	v_exp_f32_e32 v33, v33
	v_mul_f32_e32 v34, 0xbfb8aa3b, v34
	v_mul_f32_e32 v35, 0xbfb8aa3b, v35
	v_exp_f32_e32 v34, v34
	v_pk_add_f32 v[32:33], v[32:33], 1.0 op_sel_hi:[1,0]
	v_exp_f32_e32 v35, v35
	v_mul_f32_e32 v28, 0xbfb8aa3b, v28
	v_mul_f32_e32 v29, 0xbfb8aa3b, v29
	v_exp_f32_e32 v28, v28
	v_pk_add_f32 v[34:35], v[34:35], 1.0 op_sel_hi:[1,0]
	s_waitcnt lgkmcnt(0)
	v_lshlrev_b32_e32 v122, 16, v158
	v_and_b32_e32 v123, 0xffff0000, v158
	v_rcp_f32_e32 v126, v117
	v_exp_f32_e32 v29, v29
	v_mul_f32_e32 v30, 0xbfb8aa3b, v30
	v_mul_f32_e32 v31, 0xbfb8aa3b, v31
	v_mul_f32_e32 v117, 1.0, v126
	v_rcp_f32_e32 v126, v116
	v_pk_add_f32 v[28:29], v[28:29], 1.0 op_sel_hi:[1,0]
	v_exp_f32_e32 v30, v30
	v_exp_f32_e32 v31, v31
	v_mul_f32_e32 v116, 1.0, v126
	v_pk_mul_f32 v[116:117], v[116:117], v[122:123]
	v_rcp_f32_e32 v123, v119
	v_lshlrev_b32_e32 v120, 16, v159
	v_and_b32_e32 v121, 0xffff0000, v159
	v_cvt_pk_bf16_f32 v116, v116, v117
	v_mul_f32_e32 v119, 1.0, v123
	v_rcp_f32_e32 v123, v118
	v_pk_add_f32 v[30:31], v[30:31], 1.0 op_sel_hi:[1,0]
	v_mul_f32_e32 v24, 0xbfb8aa3b, v24
	v_mul_f32_e32 v25, 0xbfb8aa3b, v25
	v_mul_f32_e32 v118, 1.0, v123
	v_pk_mul_f32 v[118:119], v[118:119], v[120:121]
	v_exp_f32_e32 v24, v24
	v_cvt_pk_bf16_f32 v117, v118, v119
	global_store_dwordx2 v[124:125], v[116:117], off offset:256
	v_exp_f32_e32 v25, v25
	v_mul_f32_e32 v26, 0xbfb8aa3b, v26
	v_mul_f32_e32 v27, 0xbfb8aa3b, v27
	v_exp_f32_e32 v26, v26
	v_pk_add_f32 v[24:25], v[24:25], 1.0 op_sel_hi:[1,0]
	v_exp_f32_e32 v27, v27
	v_mul_f32_e32 v20, 0xbfb8aa3b, v20
	v_mul_f32_e32 v21, 0xbfb8aa3b, v21
	v_exp_f32_e32 v20, v20
	v_pk_add_f32 v[26:27], v[26:27], 1.0 op_sel_hi:[1,0]
	v_exp_f32_e32 v21, v21
	v_mul_f32_e32 v22, 0xbfb8aa3b, v22
	v_mul_f32_e32 v23, 0xbfb8aa3b, v23
	v_exp_f32_e32 v22, v22
	v_pk_add_f32 v[20:21], v[20:21], 1.0 op_sel_hi:[1,0]
	v_exp_f32_e32 v23, v23
	v_mul_f32_e32 v16, 0xbfb8aa3b, v16
	v_mul_f32_e32 v17, 0xbfb8aa3b, v17
	v_exp_f32_e32 v16, v16
	v_pk_add_f32 v[22:23], v[22:23], 1.0 op_sel_hi:[1,0]
	v_exp_f32_e32 v17, v17
	v_mul_f32_e32 v18, 0xbfb8aa3b, v18
	v_mul_f32_e32 v19, 0xbfb8aa3b, v19
	v_exp_f32_e32 v18, v18
	v_pk_add_f32 v[16:17], v[16:17], 1.0 op_sel_hi:[1,0]
	v_exp_f32_e32 v19, v19
	v_mul_f32_e32 v12, 0xbfb8aa3b, v12
	v_mul_f32_e32 v13, 0xbfb8aa3b, v13
	v_exp_f32_e32 v12, v12
	v_pk_add_f32 v[18:19], v[18:19], 1.0 op_sel_hi:[1,0]
	v_exp_f32_e32 v13, v13
	v_mul_f32_e32 v14, 0xbfb8aa3b, v14
	v_mul_f32_e32 v15, 0xbfb8aa3b, v15
	v_exp_f32_e32 v14, v14
	v_pk_add_f32 v[12:13], v[12:13], 1.0 op_sel_hi:[1,0]
	v_exp_f32_e32 v15, v15
	v_mul_f32_e32 v8, 0xbfb8aa3b, v8
	v_mul_f32_e32 v9, 0xbfb8aa3b, v9
	v_exp_f32_e32 v8, v8
	v_pk_add_f32 v[14:15], v[14:15], 1.0 op_sel_hi:[1,0]
	v_exp_f32_e32 v9, v9
	v_mul_f32_e32 v10, 0xbfb8aa3b, v10
	v_mul_f32_e32 v11, 0xbfb8aa3b, v11
	v_exp_f32_e32 v10, v10
	v_pk_add_f32 v[8:9], v[8:9], 1.0 op_sel_hi:[1,0]
	v_exp_f32_e32 v11, v11
	v_mul_f32_e32 v4, 0xbfb8aa3b, v4
	v_mul_f32_e32 v5, 0xbfb8aa3b, v5
	v_exp_f32_e32 v4, v4
	v_pk_add_f32 v[10:11], v[10:11], 1.0 op_sel_hi:[1,0]
	v_exp_f32_e32 v5, v5
	v_mul_f32_e32 v6, 0xbfb8aa3b, v6
	v_mul_f32_e32 v7, 0xbfb8aa3b, v7
	v_exp_f32_e32 v6, v6
	v_pk_add_f32 v[4:5], v[4:5], 1.0 op_sel_hi:[1,0]
	v_exp_f32_e32 v7, v7
	v_mul_f32_e32 v0, 0xbfb8aa3b, v0
	v_mul_f32_e32 v1, 0xbfb8aa3b, v1
	v_exp_f32_e32 v0, v0
	v_pk_add_f32 v[6:7], v[6:7], 1.0 op_sel_hi:[1,0]
	v_exp_f32_e32 v1, v1
	v_mul_f32_e32 v2, 0xbfb8aa3b, v2
	v_mul_f32_e32 v3, 0xbfb8aa3b, v3
	v_exp_f32_e32 v2, v2
	v_pk_add_f32 v[0:1], v[0:1], 1.0 op_sel_hi:[1,0]
	v_exp_f32_e32 v3, v3
	s_mov_b32 s20, s48
	s_mov_b32 s21, s50
	s_mov_b64 s[18:19], s[52:53]
	v_pk_add_f32 v[2:3], v[2:3], 1.0 op_sel_hi:[1,0]
	s_waitcnt vmcnt(0) lgkmcnt(0)
	v_lshlrev_b32_e32 v118, 16, v160
	v_and_b32_e32 v119, 0xffff0000, v160
	v_rcp_f32_e32 v120, v113
	s_nop 0
	v_mul_f32_e32 v113, 1.0, v120
	v_rcp_f32_e32 v120, v112
	s_nop 0
	v_mul_f32_e32 v112, 1.0, v120
	v_pk_mul_f32 v[112:113], v[112:113], v[118:119]
	v_rcp_f32_e32 v119, v115
	v_lshlrev_b32_e32 v116, 16, v161
	v_and_b32_e32 v117, 0xffff0000, v161
	v_cvt_pk_bf16_f32 v112, v112, v113
	v_mul_f32_e32 v115, 1.0, v119
	v_rcp_f32_e32 v119, v114
	s_nop 0
	v_mul_f32_e32 v114, 1.0, v119
	v_pk_mul_f32 v[114:115], v[114:115], v[116:117]
	s_nop 0
	v_cvt_pk_bf16_f32 v113, v114, v115
	global_store_dwordx2 v[124:125], v[112:113], off offset:288
	v_add_u32_e32 v112, 16, v140
	v_ashrrev_i32_e32 v113, 31, v112
	v_lshlrev_b64 v[116:117], 10, v[112:113]
	v_lshlrev_b64 v[114:115], 11, v[112:113]
	v_lshl_add_u64 v[112:113], s[44:45], 0, v[116:117]
	v_lshl_add_u64 v[112:113], v[112:113], 0, v[138:139]
	global_load_dwordx2 v[116:117], v[112:113], off
	global_load_dwordx2 v[156:157], v[112:113], off offset:32
	global_load_dwordx2 v[158:159], v[112:113], off offset:256
	global_load_dwordx2 v[160:161], v[112:113], off offset:288
	s_waitcnt vmcnt(0) lgkmcnt(0)
	v_lshlrev_b32_e32 v118, 16, v116
	v_and_b32_e32 v119, 0xffff0000, v116
	v_rcp_f32_e32 v120, v109
	s_nop 0
	v_mul_f32_e32 v109, 1.0, v120
	v_rcp_f32_e32 v120, v108
	s_nop 0
	v_mul_f32_e32 v108, 1.0, v120
	v_pk_mul_f32 v[108:109], v[108:109], v[118:119]
	v_rcp_f32_e32 v119, v111
	v_lshlrev_b32_e32 v116, 16, v117
	v_and_b32_e32 v117, 0xffff0000, v117
	v_mul_f32_e32 v111, 1.0, v119
	v_rcp_f32_e32 v119, v110
	s_nop 0
	v_mul_f32_e32 v110, 1.0, v119
	v_pk_mul_f32 v[110:111], v[110:111], v[116:117]
	v_cvt_pk_bf16_f32 v116, v108, v109
	v_cvt_pk_bf16_f32 v117, v110, v111
	v_lshl_add_u64 v[108:109], s[2:3], 0, v[114:115]
	v_lshl_add_u64 v[108:109], v[108:109], 0, v[138:139]
	global_store_dwordx2 v[108:109], v[116:117], off
	s_waitcnt lgkmcnt(0)
	v_lshlrev_b32_e32 v114, 16, v156
	v_and_b32_e32 v115, 0xffff0000, v156
	v_rcp_f32_e32 v116, v105
	s_nop 0
	v_mul_f32_e32 v105, 1.0, v116
	v_rcp_f32_e32 v116, v104
	s_nop 0
	v_mul_f32_e32 v104, 1.0, v116
	v_pk_mul_f32 v[104:105], v[104:105], v[114:115]
	v_rcp_f32_e32 v115, v107
	v_lshlrev_b32_e32 v110, 16, v157
	v_and_b32_e32 v111, 0xffff0000, v157
	v_cvt_pk_bf16_f32 v104, v104, v105
	v_mul_f32_e32 v107, 1.0, v115
	v_rcp_f32_e32 v115, v106
	s_nop 0
	v_mul_f32_e32 v106, 1.0, v115
	v_pk_mul_f32 v[106:107], v[106:107], v[110:111]
	s_nop 0
	v_cvt_pk_bf16_f32 v105, v106, v107
	global_store_dwordx2 v[108:109], v[104:105], off offset:32
	s_waitcnt lgkmcnt(0)
	v_lshlrev_b32_e32 v106, 16, v158
	v_and_b32_e32 v107, 0xffff0000, v158
	v_rcp_f32_e32 v110, v101
	s_nop 0
	v_mul_f32_e32 v101, 1.0, v110
	v_rcp_f32_e32 v110, v100
	s_nop 0
	v_mul_f32_e32 v100, 1.0, v110
	v_pk_mul_f32 v[100:101], v[100:101], v[106:107]
	v_rcp_f32_e32 v107, v103
	v_lshlrev_b32_e32 v104, 16, v159
	v_and_b32_e32 v105, 0xffff0000, v159
	v_cvt_pk_bf16_f32 v100, v100, v101
	v_mul_f32_e32 v103, 1.0, v107
	v_rcp_f32_e32 v107, v102
	s_nop 0
	v_mul_f32_e32 v102, 1.0, v107
	v_pk_mul_f32 v[102:103], v[102:103], v[104:105]
	s_nop 0
	v_cvt_pk_bf16_f32 v101, v102, v103
	global_store_dwordx2 v[108:109], v[100:101], off offset:256
	s_waitcnt lgkmcnt(0)
	v_lshlrev_b32_e32 v102, 16, v160
	v_and_b32_e32 v103, 0xffff0000, v160
	v_rcp_f32_e32 v104, v97
	s_nop 0
	v_mul_f32_e32 v97, 1.0, v104
	v_rcp_f32_e32 v104, v96
	s_nop 0
	v_mul_f32_e32 v96, 1.0, v104
	v_pk_mul_f32 v[96:97], v[96:97], v[102:103]
	v_rcp_f32_e32 v103, v99
	v_lshlrev_b32_e32 v100, 16, v161
	v_and_b32_e32 v101, 0xffff0000, v161
	v_cvt_pk_bf16_f32 v96, v96, v97
	v_mul_f32_e32 v99, 1.0, v103
	v_rcp_f32_e32 v103, v98
	s_nop 0
	v_mul_f32_e32 v98, 1.0, v103
	v_pk_mul_f32 v[98:99], v[98:99], v[100:101]
	s_nop 0
	v_cvt_pk_bf16_f32 v97, v98, v99
	global_store_dwordx2 v[108:109], v[96:97], off offset:288
	v_add_u32_e32 v96, 32, v140
	v_ashrrev_i32_e32 v97, 31, v96
	v_lshlrev_b64 v[100:101], 10, v[96:97]
	v_lshlrev_b64 v[98:99], 11, v[96:97]
	v_lshl_add_u64 v[96:97], s[44:45], 0, v[100:101]
	v_lshl_add_u64 v[96:97], v[96:97], 0, v[138:139]
	global_load_dwordx2 v[100:101], v[96:97], off
	global_load_dwordx2 v[156:157], v[96:97], off offset:32
	global_load_dwordx2 v[158:159], v[96:97], off offset:256
	global_load_dwordx2 v[160:161], v[96:97], off offset:288
	s_waitcnt vmcnt(0) lgkmcnt(0)
	v_lshlrev_b32_e32 v102, 16, v100
	v_and_b32_e32 v103, 0xffff0000, v100
	v_rcp_f32_e32 v104, v93
	s_nop 0
	v_mul_f32_e32 v93, 1.0, v104
	v_rcp_f32_e32 v104, v92
	s_nop 0
	v_mul_f32_e32 v92, 1.0, v104
	v_pk_mul_f32 v[92:93], v[92:93], v[102:103]
	v_rcp_f32_e32 v103, v95
	v_lshlrev_b32_e32 v100, 16, v101
	v_and_b32_e32 v101, 0xffff0000, v101
	v_mul_f32_e32 v95, 1.0, v103
	v_rcp_f32_e32 v103, v94
	s_nop 0
	v_mul_f32_e32 v94, 1.0, v103
	v_pk_mul_f32 v[94:95], v[94:95], v[100:101]
	v_cvt_pk_bf16_f32 v100, v92, v93
	v_cvt_pk_bf16_f32 v101, v94, v95
	v_lshl_add_u64 v[92:93], s[2:3], 0, v[98:99]
	v_lshl_add_u64 v[92:93], v[92:93], 0, v[138:139]
	global_store_dwordx2 v[92:93], v[100:101], off
	s_waitcnt lgkmcnt(0)
	v_lshlrev_b32_e32 v98, 16, v156
	v_and_b32_e32 v99, 0xffff0000, v156
	v_rcp_f32_e32 v100, v89
	s_nop 0
	v_mul_f32_e32 v89, 1.0, v100
	v_rcp_f32_e32 v100, v88
	s_nop 0
	v_mul_f32_e32 v88, 1.0, v100
	v_pk_mul_f32 v[88:89], v[88:89], v[98:99]
	v_rcp_f32_e32 v99, v91
	v_lshlrev_b32_e32 v94, 16, v157
	v_and_b32_e32 v95, 0xffff0000, v157
	v_cvt_pk_bf16_f32 v88, v88, v89
	v_mul_f32_e32 v91, 1.0, v99
	v_rcp_f32_e32 v99, v90
	s_nop 0
	v_mul_f32_e32 v90, 1.0, v99
	v_pk_mul_f32 v[90:91], v[90:91], v[94:95]
	s_nop 0
	v_cvt_pk_bf16_f32 v89, v90, v91
	global_store_dwordx2 v[92:93], v[88:89], off offset:32
	s_waitcnt lgkmcnt(0)
	v_lshlrev_b32_e32 v90, 16, v158
	v_and_b32_e32 v91, 0xffff0000, v158
	v_rcp_f32_e32 v94, v85
	s_nop 0
	v_mul_f32_e32 v85, 1.0, v94
	v_rcp_f32_e32 v94, v84
	s_nop 0
	v_mul_f32_e32 v84, 1.0, v94
	v_pk_mul_f32 v[84:85], v[84:85], v[90:91]
	v_rcp_f32_e32 v91, v87
	v_lshlrev_b32_e32 v88, 16, v159
	v_and_b32_e32 v89, 0xffff0000, v159
	v_cvt_pk_bf16_f32 v84, v84, v85
	v_mul_f32_e32 v87, 1.0, v91
	v_rcp_f32_e32 v91, v86
	s_nop 0
	v_mul_f32_e32 v86, 1.0, v91
	v_pk_mul_f32 v[86:87], v[86:87], v[88:89]
	s_nop 0
	v_cvt_pk_bf16_f32 v85, v86, v87
	global_store_dwordx2 v[92:93], v[84:85], off offset:256
	s_waitcnt lgkmcnt(0)
	v_lshlrev_b32_e32 v86, 16, v160
	v_and_b32_e32 v87, 0xffff0000, v160
	v_rcp_f32_e32 v88, v81
	s_nop 0
	v_mul_f32_e32 v81, 1.0, v88
	v_rcp_f32_e32 v88, v80
	s_nop 0
	v_mul_f32_e32 v80, 1.0, v88
	v_pk_mul_f32 v[80:81], v[80:81], v[86:87]
	v_rcp_f32_e32 v87, v83
	v_lshlrev_b32_e32 v84, 16, v161
	v_and_b32_e32 v85, 0xffff0000, v161
	v_cvt_pk_bf16_f32 v80, v80, v81
	v_mul_f32_e32 v83, 1.0, v87
	v_rcp_f32_e32 v87, v82
	s_nop 0
	v_mul_f32_e32 v82, 1.0, v87
	v_pk_mul_f32 v[82:83], v[82:83], v[84:85]
	s_nop 0
	v_cvt_pk_bf16_f32 v81, v82, v83
	global_store_dwordx2 v[92:93], v[80:81], off offset:288
	v_add_u32_e32 v80, 48, v140
	v_ashrrev_i32_e32 v81, 31, v80
	v_lshlrev_b64 v[84:85], 10, v[80:81]
	v_lshlrev_b64 v[82:83], 11, v[80:81]
	v_lshl_add_u64 v[80:81], s[44:45], 0, v[84:85]
	v_lshl_add_u64 v[80:81], v[80:81], 0, v[138:139]
	global_load_dwordx2 v[84:85], v[80:81], off
	global_load_dwordx2 v[156:157], v[80:81], off offset:32
	global_load_dwordx2 v[158:159], v[80:81], off offset:256
	global_load_dwordx2 v[160:161], v[80:81], off offset:288
	s_waitcnt vmcnt(0) lgkmcnt(0)
	v_lshlrev_b32_e32 v86, 16, v84
	v_and_b32_e32 v87, 0xffff0000, v84
	v_rcp_f32_e32 v88, v77
	s_nop 0
	v_mul_f32_e32 v77, 1.0, v88
	v_rcp_f32_e32 v88, v76
	s_nop 0
	v_mul_f32_e32 v76, 1.0, v88
	v_pk_mul_f32 v[76:77], v[76:77], v[86:87]
	v_rcp_f32_e32 v87, v79
	v_lshlrev_b32_e32 v84, 16, v85
	v_and_b32_e32 v85, 0xffff0000, v85
	v_mul_f32_e32 v79, 1.0, v87
	v_rcp_f32_e32 v87, v78
	s_nop 0
	v_mul_f32_e32 v78, 1.0, v87
	v_pk_mul_f32 v[78:79], v[78:79], v[84:85]
	v_cvt_pk_bf16_f32 v84, v76, v77
	v_cvt_pk_bf16_f32 v85, v78, v79
	v_lshl_add_u64 v[76:77], s[2:3], 0, v[82:83]
	v_lshl_add_u64 v[76:77], v[76:77], 0, v[138:139]
	global_store_dwordx2 v[76:77], v[84:85], off
	s_waitcnt lgkmcnt(0)
	v_lshlrev_b32_e32 v82, 16, v156
	v_and_b32_e32 v83, 0xffff0000, v156
	v_rcp_f32_e32 v84, v73
	s_nop 0
	v_mul_f32_e32 v73, 1.0, v84
	v_rcp_f32_e32 v84, v72
	s_nop 0
	v_mul_f32_e32 v72, 1.0, v84
	v_pk_mul_f32 v[72:73], v[72:73], v[82:83]
	v_rcp_f32_e32 v83, v75
	v_lshlrev_b32_e32 v78, 16, v157
	v_and_b32_e32 v79, 0xffff0000, v157
	v_cvt_pk_bf16_f32 v72, v72, v73
	v_mul_f32_e32 v75, 1.0, v83
	v_rcp_f32_e32 v83, v74
	s_nop 0
	v_mul_f32_e32 v74, 1.0, v83
	v_pk_mul_f32 v[74:75], v[74:75], v[78:79]
	s_nop 0
	v_cvt_pk_bf16_f32 v73, v74, v75
	global_store_dwordx2 v[76:77], v[72:73], off offset:32
	s_waitcnt lgkmcnt(0)
	v_lshlrev_b32_e32 v74, 16, v158
	v_and_b32_e32 v75, 0xffff0000, v158
	v_rcp_f32_e32 v78, v69
	s_nop 0
	v_mul_f32_e32 v69, 1.0, v78
	v_rcp_f32_e32 v78, v68
	s_nop 0
	v_mul_f32_e32 v68, 1.0, v78
	v_pk_mul_f32 v[68:69], v[68:69], v[74:75]
	v_rcp_f32_e32 v75, v71
	v_lshlrev_b32_e32 v72, 16, v159
	v_and_b32_e32 v73, 0xffff0000, v159
	v_cvt_pk_bf16_f32 v68, v68, v69
	v_mul_f32_e32 v71, 1.0, v75
	v_rcp_f32_e32 v75, v70
	s_nop 0
	v_mul_f32_e32 v70, 1.0, v75
	v_pk_mul_f32 v[70:71], v[70:71], v[72:73]
	s_nop 0
	v_cvt_pk_bf16_f32 v69, v70, v71
	global_store_dwordx2 v[76:77], v[68:69], off offset:256
	s_waitcnt lgkmcnt(0)
	v_lshlrev_b32_e32 v70, 16, v160
	v_and_b32_e32 v71, 0xffff0000, v160
	v_rcp_f32_e32 v72, v65
	s_nop 0
	v_mul_f32_e32 v65, 1.0, v72
	v_rcp_f32_e32 v72, v64
	s_nop 0
	v_mul_f32_e32 v64, 1.0, v72
	v_pk_mul_f32 v[64:65], v[64:65], v[70:71]
	v_rcp_f32_e32 v71, v67
	v_lshlrev_b32_e32 v68, 16, v161
	v_and_b32_e32 v69, 0xffff0000, v161
	v_cvt_pk_bf16_f32 v64, v64, v65
	v_mul_f32_e32 v67, 1.0, v71
	v_rcp_f32_e32 v71, v66
	s_nop 0
	v_mul_f32_e32 v66, 1.0, v71
	v_pk_mul_f32 v[66:67], v[66:67], v[68:69]
	s_nop 0
	v_cvt_pk_bf16_f32 v65, v66, v67
	global_store_dwordx2 v[76:77], v[64:65], off offset:288
	v_add_u32_e32 v64, 0x80, v140
	v_ashrrev_i32_e32 v65, 31, v64
	v_lshlrev_b64 v[68:69], 10, v[64:65]
	v_lshlrev_b64 v[66:67], 11, v[64:65]
	v_lshl_add_u64 v[64:65], s[44:45], 0, v[68:69]
	v_lshl_add_u64 v[64:65], v[64:65], 0, v[138:139]
	global_load_dwordx2 v[68:69], v[64:65], off
	global_load_dwordx2 v[156:157], v[64:65], off offset:32
	global_load_dwordx2 v[158:159], v[64:65], off offset:256
	global_load_dwordx2 v[160:161], v[64:65], off offset:288
	s_waitcnt vmcnt(0) lgkmcnt(0)
	v_lshlrev_b32_e32 v70, 16, v68
	v_and_b32_e32 v71, 0xffff0000, v68
	v_rcp_f32_e32 v72, v61
	s_nop 0
	v_mul_f32_e32 v61, 1.0, v72
	v_rcp_f32_e32 v72, v60
	s_nop 0
	v_mul_f32_e32 v60, 1.0, v72
	v_pk_mul_f32 v[60:61], v[60:61], v[70:71]
	v_rcp_f32_e32 v71, v63
	v_lshlrev_b32_e32 v68, 16, v69
	v_and_b32_e32 v69, 0xffff0000, v69
	v_mul_f32_e32 v63, 1.0, v71
	v_rcp_f32_e32 v71, v62
	s_nop 0
	v_mul_f32_e32 v62, 1.0, v71
	v_pk_mul_f32 v[62:63], v[62:63], v[68:69]
	v_cvt_pk_bf16_f32 v68, v60, v61
	v_cvt_pk_bf16_f32 v69, v62, v63
	v_lshl_add_u64 v[60:61], s[2:3], 0, v[66:67]
	v_lshl_add_u64 v[60:61], v[60:61], 0, v[138:139]
	global_store_dwordx2 v[60:61], v[68:69], off
	s_waitcnt lgkmcnt(0)
	v_lshlrev_b32_e32 v66, 16, v156
	v_and_b32_e32 v67, 0xffff0000, v156
	v_rcp_f32_e32 v68, v57
	s_nop 0
	v_mul_f32_e32 v57, 1.0, v68
	v_rcp_f32_e32 v68, v56
	s_nop 0
	v_mul_f32_e32 v56, 1.0, v68
	v_pk_mul_f32 v[56:57], v[56:57], v[66:67]
	v_rcp_f32_e32 v67, v59
	v_lshlrev_b32_e32 v62, 16, v157
	v_and_b32_e32 v63, 0xffff0000, v157
	v_cvt_pk_bf16_f32 v56, v56, v57
	v_mul_f32_e32 v59, 1.0, v67
	v_rcp_f32_e32 v67, v58
	s_nop 0
	v_mul_f32_e32 v58, 1.0, v67
	v_pk_mul_f32 v[58:59], v[58:59], v[62:63]
	s_nop 0
	v_cvt_pk_bf16_f32 v57, v58, v59
	global_store_dwordx2 v[60:61], v[56:57], off offset:32
	s_waitcnt lgkmcnt(0)
	v_lshlrev_b32_e32 v58, 16, v158
	v_and_b32_e32 v59, 0xffff0000, v158
	v_rcp_f32_e32 v62, v53
	s_nop 0
	v_mul_f32_e32 v53, 1.0, v62
	v_rcp_f32_e32 v62, v52
	s_nop 0
	v_mul_f32_e32 v52, 1.0, v62
	v_pk_mul_f32 v[52:53], v[52:53], v[58:59]
	v_rcp_f32_e32 v59, v55
	v_lshlrev_b32_e32 v56, 16, v159
	v_and_b32_e32 v57, 0xffff0000, v159
	v_cvt_pk_bf16_f32 v52, v52, v53
	v_mul_f32_e32 v55, 1.0, v59
	v_rcp_f32_e32 v59, v54
	s_nop 0
	v_mul_f32_e32 v54, 1.0, v59
	v_pk_mul_f32 v[54:55], v[54:55], v[56:57]
	s_nop 0
	v_cvt_pk_bf16_f32 v53, v54, v55
	global_store_dwordx2 v[60:61], v[52:53], off offset:256
	s_waitcnt lgkmcnt(0)
	v_lshlrev_b32_e32 v54, 16, v160
	v_and_b32_e32 v55, 0xffff0000, v160
	v_rcp_f32_e32 v56, v49
	s_nop 0
	v_mul_f32_e32 v49, 1.0, v56
	v_rcp_f32_e32 v56, v48
	s_nop 0
	v_mul_f32_e32 v48, 1.0, v56
	v_pk_mul_f32 v[48:49], v[48:49], v[54:55]
	v_rcp_f32_e32 v55, v51
	v_lshlrev_b32_e32 v52, 16, v161
	v_and_b32_e32 v53, 0xffff0000, v161
	v_cvt_pk_bf16_f32 v48, v48, v49
	v_mul_f32_e32 v51, 1.0, v55
	v_rcp_f32_e32 v55, v50
	s_nop 0
	v_mul_f32_e32 v50, 1.0, v55
	v_pk_mul_f32 v[50:51], v[50:51], v[52:53]
	s_nop 0
	v_cvt_pk_bf16_f32 v49, v50, v51
	global_store_dwordx2 v[60:61], v[48:49], off offset:288
	v_add_u32_e32 v48, 0x90, v140
	v_ashrrev_i32_e32 v49, 31, v48
	v_lshlrev_b64 v[52:53], 10, v[48:49]
	v_lshlrev_b64 v[50:51], 11, v[48:49]
	v_lshl_add_u64 v[48:49], s[44:45], 0, v[52:53]
	v_lshl_add_u64 v[48:49], v[48:49], 0, v[138:139]
	global_load_dwordx2 v[52:53], v[48:49], off
	global_load_dwordx2 v[156:157], v[48:49], off offset:32
	global_load_dwordx2 v[158:159], v[48:49], off offset:256
	global_load_dwordx2 v[160:161], v[48:49], off offset:288
	s_waitcnt vmcnt(0) lgkmcnt(0)
	v_lshlrev_b32_e32 v54, 16, v52
	v_and_b32_e32 v55, 0xffff0000, v52
	v_rcp_f32_e32 v56, v45
	s_nop 0
	v_mul_f32_e32 v45, 1.0, v56
	v_rcp_f32_e32 v56, v44
	s_nop 0
	v_mul_f32_e32 v44, 1.0, v56
	v_pk_mul_f32 v[44:45], v[44:45], v[54:55]
	v_rcp_f32_e32 v55, v47
	v_lshlrev_b32_e32 v52, 16, v53
	v_and_b32_e32 v53, 0xffff0000, v53
	v_mul_f32_e32 v47, 1.0, v55
	v_rcp_f32_e32 v55, v46
	s_nop 0
	v_mul_f32_e32 v46, 1.0, v55
	v_pk_mul_f32 v[46:47], v[46:47], v[52:53]
	v_cvt_pk_bf16_f32 v52, v44, v45
	v_cvt_pk_bf16_f32 v53, v46, v47
	v_lshl_add_u64 v[44:45], s[2:3], 0, v[50:51]
	v_lshl_add_u64 v[44:45], v[44:45], 0, v[138:139]
	global_store_dwordx2 v[44:45], v[52:53], off
	s_waitcnt lgkmcnt(0)
	v_lshlrev_b32_e32 v50, 16, v156
	v_and_b32_e32 v51, 0xffff0000, v156
	v_rcp_f32_e32 v52, v41
	s_nop 0
	v_mul_f32_e32 v41, 1.0, v52
	v_rcp_f32_e32 v52, v40
	s_nop 0
	v_mul_f32_e32 v40, 1.0, v52
	v_pk_mul_f32 v[40:41], v[40:41], v[50:51]
	v_rcp_f32_e32 v51, v43
	v_lshlrev_b32_e32 v46, 16, v157
	v_and_b32_e32 v47, 0xffff0000, v157
	v_cvt_pk_bf16_f32 v40, v40, v41
	v_mul_f32_e32 v43, 1.0, v51
	v_rcp_f32_e32 v51, v42
	s_nop 0
	v_mul_f32_e32 v42, 1.0, v51
	v_pk_mul_f32 v[42:43], v[42:43], v[46:47]
	s_nop 0
	v_cvt_pk_bf16_f32 v41, v42, v43
	global_store_dwordx2 v[44:45], v[40:41], off offset:32
	s_waitcnt lgkmcnt(0)
	v_lshlrev_b32_e32 v42, 16, v158
	v_and_b32_e32 v43, 0xffff0000, v158
	v_rcp_f32_e32 v46, v37
	s_nop 0
	v_mul_f32_e32 v37, 1.0, v46
	v_rcp_f32_e32 v46, v36
	s_nop 0
	v_mul_f32_e32 v36, 1.0, v46
	v_pk_mul_f32 v[36:37], v[36:37], v[42:43]
	v_rcp_f32_e32 v43, v39
	v_lshlrev_b32_e32 v40, 16, v159
	v_and_b32_e32 v41, 0xffff0000, v159
	v_cvt_pk_bf16_f32 v36, v36, v37
	v_mul_f32_e32 v39, 1.0, v43
	v_rcp_f32_e32 v43, v38
	s_nop 0
	v_mul_f32_e32 v38, 1.0, v43
	v_pk_mul_f32 v[38:39], v[38:39], v[40:41]
	s_nop 0
	v_cvt_pk_bf16_f32 v37, v38, v39
	global_store_dwordx2 v[44:45], v[36:37], off offset:256
	s_waitcnt lgkmcnt(0)
	v_lshlrev_b32_e32 v38, 16, v160
	v_and_b32_e32 v39, 0xffff0000, v160
	v_rcp_f32_e32 v40, v33
	s_nop 0
	v_mul_f32_e32 v33, 1.0, v40
	v_rcp_f32_e32 v40, v32
	s_nop 0
	v_mul_f32_e32 v32, 1.0, v40
	v_pk_mul_f32 v[32:33], v[32:33], v[38:39]
	v_rcp_f32_e32 v39, v35
	v_lshlrev_b32_e32 v36, 16, v161
	v_and_b32_e32 v37, 0xffff0000, v161
	v_cvt_pk_bf16_f32 v32, v32, v33
	v_mul_f32_e32 v35, 1.0, v39
	v_rcp_f32_e32 v39, v34
	s_nop 0
	v_mul_f32_e32 v34, 1.0, v39
	v_pk_mul_f32 v[34:35], v[34:35], v[36:37]
	s_nop 0
	v_cvt_pk_bf16_f32 v33, v34, v35
	global_store_dwordx2 v[44:45], v[32:33], off offset:288
	v_add_u32_e32 v32, 0xa0, v140
	v_ashrrev_i32_e32 v33, 31, v32
	v_lshlrev_b64 v[36:37], 10, v[32:33]
	v_lshlrev_b64 v[34:35], 11, v[32:33]
	v_lshl_add_u64 v[32:33], s[44:45], 0, v[36:37]
	v_lshl_add_u64 v[32:33], v[32:33], 0, v[138:139]
	global_load_dwordx2 v[36:37], v[32:33], off
	global_load_dwordx2 v[156:157], v[32:33], off offset:32
	global_load_dwordx2 v[158:159], v[32:33], off offset:256
	global_load_dwordx2 v[160:161], v[32:33], off offset:288
	s_waitcnt vmcnt(0) lgkmcnt(0)
	v_lshlrev_b32_e32 v38, 16, v36
	v_and_b32_e32 v39, 0xffff0000, v36
	v_rcp_f32_e32 v40, v29
	s_nop 0
	v_mul_f32_e32 v29, 1.0, v40
	v_rcp_f32_e32 v40, v28
	s_nop 0
	v_mul_f32_e32 v28, 1.0, v40
	v_pk_mul_f32 v[28:29], v[28:29], v[38:39]
	v_rcp_f32_e32 v39, v31
	v_lshlrev_b32_e32 v36, 16, v37
	v_and_b32_e32 v37, 0xffff0000, v37
	v_mul_f32_e32 v31, 1.0, v39
	v_rcp_f32_e32 v39, v30
	s_nop 0
	v_mul_f32_e32 v30, 1.0, v39
	v_pk_mul_f32 v[30:31], v[30:31], v[36:37]
	v_cvt_pk_bf16_f32 v36, v28, v29
	v_cvt_pk_bf16_f32 v37, v30, v31
	v_lshl_add_u64 v[28:29], s[2:3], 0, v[34:35]
	v_lshl_add_u64 v[28:29], v[28:29], 0, v[138:139]
	global_store_dwordx2 v[28:29], v[36:37], off
	s_waitcnt lgkmcnt(0)
	v_lshlrev_b32_e32 v34, 16, v156
	v_and_b32_e32 v35, 0xffff0000, v156
	v_rcp_f32_e32 v36, v25
	s_nop 0
	v_mul_f32_e32 v25, 1.0, v36
	v_rcp_f32_e32 v36, v24
	s_nop 0
	v_mul_f32_e32 v24, 1.0, v36
	v_pk_mul_f32 v[24:25], v[24:25], v[34:35]
	v_rcp_f32_e32 v35, v27
	v_lshlrev_b32_e32 v30, 16, v157
	v_and_b32_e32 v31, 0xffff0000, v157
	v_cvt_pk_bf16_f32 v24, v24, v25
	v_mul_f32_e32 v27, 1.0, v35
	v_rcp_f32_e32 v35, v26
	s_nop 0
	v_mul_f32_e32 v26, 1.0, v35
	v_pk_mul_f32 v[26:27], v[26:27], v[30:31]
	s_nop 0
	v_cvt_pk_bf16_f32 v25, v26, v27
	global_store_dwordx2 v[28:29], v[24:25], off offset:32
	s_waitcnt lgkmcnt(0)
	v_lshlrev_b32_e32 v26, 16, v158
	v_and_b32_e32 v27, 0xffff0000, v158
	v_rcp_f32_e32 v30, v21
	s_nop 0
	v_mul_f32_e32 v21, 1.0, v30
	v_rcp_f32_e32 v30, v20
	s_nop 0
	v_mul_f32_e32 v20, 1.0, v30
	v_pk_mul_f32 v[20:21], v[20:21], v[26:27]
	v_rcp_f32_e32 v27, v23
	v_lshlrev_b32_e32 v24, 16, v159
	v_and_b32_e32 v25, 0xffff0000, v159
	v_cvt_pk_bf16_f32 v20, v20, v21
	v_mul_f32_e32 v23, 1.0, v27
	v_rcp_f32_e32 v27, v22
	s_nop 0
	v_mul_f32_e32 v22, 1.0, v27
	v_pk_mul_f32 v[22:23], v[22:23], v[24:25]
	s_nop 0
	v_cvt_pk_bf16_f32 v21, v22, v23
	global_store_dwordx2 v[28:29], v[20:21], off offset:256
	s_waitcnt lgkmcnt(0)
	v_lshlrev_b32_e32 v22, 16, v160
	v_and_b32_e32 v23, 0xffff0000, v160
	v_rcp_f32_e32 v24, v17
	s_nop 0
	v_mul_f32_e32 v17, 1.0, v24
	v_rcp_f32_e32 v24, v16
	s_nop 0
	v_mul_f32_e32 v16, 1.0, v24
	v_pk_mul_f32 v[16:17], v[16:17], v[22:23]
	v_rcp_f32_e32 v23, v19
	v_lshlrev_b32_e32 v20, 16, v161
	v_and_b32_e32 v21, 0xffff0000, v161
	v_cvt_pk_bf16_f32 v16, v16, v17
	v_mul_f32_e32 v19, 1.0, v23
	v_rcp_f32_e32 v23, v18
	s_nop 0
	v_mul_f32_e32 v18, 1.0, v23
	v_pk_mul_f32 v[18:19], v[18:19], v[20:21]
	s_nop 0
	v_cvt_pk_bf16_f32 v17, v18, v19
	global_store_dwordx2 v[28:29], v[16:17], off offset:288
	v_add_u32_e32 v16, 0xb0, v140
	v_ashrrev_i32_e32 v17, 31, v16
	v_lshlrev_b64 v[20:21], 10, v[16:17]
	v_lshlrev_b64 v[18:19], 11, v[16:17]
	v_lshl_add_u64 v[16:17], s[44:45], 0, v[20:21]
	v_lshl_add_u64 v[16:17], v[16:17], 0, v[138:139]
	global_load_dwordx2 v[20:21], v[16:17], off
	global_load_dwordx2 v[156:157], v[16:17], off offset:32
	global_load_dwordx2 v[158:159], v[16:17], off offset:256
	global_load_dwordx2 v[160:161], v[16:17], off offset:288
	s_waitcnt vmcnt(0) lgkmcnt(0)
	v_lshlrev_b32_e32 v22, 16, v20
	v_and_b32_e32 v23, 0xffff0000, v20
	v_rcp_f32_e32 v24, v13
	s_nop 0
	v_mul_f32_e32 v13, 1.0, v24
	v_rcp_f32_e32 v24, v12
	s_nop 0
	v_mul_f32_e32 v12, 1.0, v24
	v_pk_mul_f32 v[12:13], v[12:13], v[22:23]
	v_rcp_f32_e32 v23, v15
	v_lshlrev_b32_e32 v20, 16, v21
	v_and_b32_e32 v21, 0xffff0000, v21
	v_mul_f32_e32 v15, 1.0, v23
	v_rcp_f32_e32 v23, v14
	s_nop 0
	v_mul_f32_e32 v14, 1.0, v23
	v_pk_mul_f32 v[14:15], v[14:15], v[20:21]
	v_cvt_pk_bf16_f32 v20, v12, v13
	v_cvt_pk_bf16_f32 v21, v14, v15
	v_lshl_add_u64 v[12:13], s[2:3], 0, v[18:19]
	v_lshl_add_u64 v[12:13], v[12:13], 0, v[138:139]
	global_store_dwordx2 v[12:13], v[20:21], off
	s_mov_b64 s[2:3], s[54:55]
	s_waitcnt lgkmcnt(0)
	v_lshlrev_b32_e32 v18, 16, v156
	v_and_b32_e32 v19, 0xffff0000, v156
	v_rcp_f32_e32 v20, v9
	s_nop 0
	v_mul_f32_e32 v9, 1.0, v20
	v_rcp_f32_e32 v20, v8
	s_nop 0
	v_mul_f32_e32 v8, 1.0, v20
	v_pk_mul_f32 v[8:9], v[8:9], v[18:19]
	v_rcp_f32_e32 v19, v11
	v_lshlrev_b32_e32 v14, 16, v157
	v_and_b32_e32 v15, 0xffff0000, v157
	v_cvt_pk_bf16_f32 v8, v8, v9
	v_mul_f32_e32 v11, 1.0, v19
	v_rcp_f32_e32 v19, v10
	s_nop 0
	v_mul_f32_e32 v10, 1.0, v19
	v_pk_mul_f32 v[10:11], v[10:11], v[14:15]
	s_nop 0
	v_cvt_pk_bf16_f32 v9, v10, v11
	global_store_dwordx2 v[12:13], v[8:9], off offset:32
	s_waitcnt lgkmcnt(0)
	v_lshlrev_b32_e32 v10, 16, v158
	v_and_b32_e32 v11, 0xffff0000, v158
	v_rcp_f32_e32 v14, v5
	s_nop 0
	v_mul_f32_e32 v5, 1.0, v14
	v_rcp_f32_e32 v14, v4
	s_nop 0
	v_mul_f32_e32 v4, 1.0, v14
	v_pk_mul_f32 v[4:5], v[4:5], v[10:11]
	v_rcp_f32_e32 v11, v7
	v_lshlrev_b32_e32 v8, 16, v159
	v_and_b32_e32 v9, 0xffff0000, v159
	v_cvt_pk_bf16_f32 v4, v4, v5
	v_mul_f32_e32 v7, 1.0, v11
	v_rcp_f32_e32 v11, v6
	s_nop 0
	v_mul_f32_e32 v6, 1.0, v11
	v_pk_mul_f32 v[6:7], v[6:7], v[8:9]
	s_nop 0
	v_cvt_pk_bf16_f32 v5, v6, v7
	global_store_dwordx2 v[12:13], v[4:5], off offset:256
	s_waitcnt lgkmcnt(0)
	v_lshlrev_b32_e32 v6, 16, v160
	v_and_b32_e32 v7, 0xffff0000, v160
	v_rcp_f32_e32 v8, v1
	s_nop 0
	v_mul_f32_e32 v1, 1.0, v8
	v_rcp_f32_e32 v8, v0
	s_nop 0
	v_mul_f32_e32 v0, 1.0, v8
	v_pk_mul_f32 v[0:1], v[0:1], v[6:7]
	v_rcp_f32_e32 v7, v3
	v_lshlrev_b32_e32 v4, 16, v161
	v_and_b32_e32 v5, 0xffff0000, v161
	v_cvt_pk_bf16_f32 v0, v0, v1
	v_mul_f32_e32 v3, 1.0, v7
	s_nop 0
	v_rcp_f32_e32 v7, v2
	s_nop 8
	v_mul_f32_e32 v2, 1.0, v7
	v_pk_mul_f32 v[2:3], v[2:3], v[4:5]
	s_and_b64 vcc, exec, s[42:43]
	v_cvt_pk_bf16_f32 v1, v2, v3
	global_store_dwordx2 v[12:13], v[0:1], off offset:288
	s_cbranch_vccnz .LBB0_1978

.LBB0_2476:
	s_or_b64 exec, exec, s[8:9]
	v_add_u32_e32 v166, s48, v165
	v_ashrrev_i32_e32 v167, 31, v166
	v_lshlrev_b64 v[170:171], 2, v[166:167]
	v_lshl_add_u64 v[172:173], v[160:161], 0, v[170:171]
	global_load_dwordx4 v[166:169], v[172:173], off
	global_load_dwordx4 v[176:179], v[172:173], off offset:64
	global_load_dwordx4 v[180:183], v[172:173], off offset:512
	global_load_dwordx4 v[184:187], v[172:173], off offset:576
	v_readlane_b32 s8, v255, 10
	v_readlane_b32 s9, v255, 11
	s_waitcnt vmcnt(0) lgkmcnt(0)
	v_pk_fma_f32 v[160:161], v[144:145], v[126:127], v[168:169]
	v_lshl_add_u64 v[158:159], s[8:9], 0, v[158:159]
	v_lshl_add_u64 v[170:171], v[158:159], 0, v[170:171]
	v_pk_fma_f32 v[158:159], v[142:143], v[124:125], v[166:167]
	global_store_dwordx4 v[170:171], v[158:161], off
	s_mov_b64 s[8:9], 0
	s_waitcnt lgkmcnt(0)
	v_pk_fma_f32 v[160:161], v[140:141], v[122:123], v[178:179]
	v_pk_fma_f32 v[158:159], v[138:139], v[120:121], v[176:177]
	global_store_dwordx4 v[170:171], v[158:161], off offset:64
	s_waitcnt lgkmcnt(0)
	s_nop 0
	v_pk_fma_f32 v[160:161], v[136:137], v[118:119], v[182:183]
	v_pk_fma_f32 v[158:159], v[134:135], v[116:117], v[180:181]
	global_store_dwordx4 v[170:171], v[158:161], off offset:512
	s_waitcnt lgkmcnt(0)
	s_nop 0
	v_pk_fma_f32 v[160:161], v[132:133], v[114:115], v[186:187]
	v_pk_fma_f32 v[158:159], v[130:131], v[112:113], v[184:185]
	global_store_dwordx4 v[170:171], v[158:161], off offset:576

.LBB0_2484:
	s_or_b64 exec, exec, s[8:9]
	v_add_u32_e32 v134, s48, v165
	v_ashrrev_i32_e32 v135, 31, v134
	v_lshlrev_b64 v[136:137], 2, v[134:135]
	v_lshl_add_u64 v[138:139], v[132:133], 0, v[136:137]
	global_load_dwordx4 v[132:135], v[138:139], off
	global_load_dwordx4 v[176:179], v[138:139], off offset:64
	global_load_dwordx4 v[180:183], v[138:139], off offset:512
	global_load_dwordx4 v[184:187], v[138:139], off offset:576
	v_readlane_b32 s8, v255, 10
	v_readlane_b32 s9, v255, 11
	s_waitcnt vmcnt(0) lgkmcnt(0)
	v_pk_fma_f32 v[134:135], v[110:111], v[126:127], v[134:135]
	v_lshl_add_u64 v[130:131], s[8:9], 0, v[130:131]
	v_lshl_add_u64 v[136:137], v[130:131], 0, v[136:137]
	v_pk_fma_f32 v[132:133], v[108:109], v[124:125], v[132:133]
	global_store_dwordx4 v[136:137], v[132:135], off
	s_waitcnt lgkmcnt(0)
	s_nop 0
	v_pk_fma_f32 v[132:133], v[106:107], v[122:123], v[178:179]
	v_pk_fma_f32 v[130:131], v[104:105], v[120:121], v[176:177]
	global_store_dwordx4 v[136:137], v[130:133], off offset:64
	s_waitcnt lgkmcnt(0)
	s_nop 0
	v_pk_fma_f32 v[132:133], v[102:103], v[118:119], v[182:183]
	v_pk_fma_f32 v[130:131], v[100:101], v[116:117], v[180:181]
	global_store_dwordx4 v[136:137], v[130:133], off offset:512
	s_waitcnt lgkmcnt(0)
	s_nop 0
	v_pk_fma_f32 v[132:133], v[98:99], v[114:115], v[186:187]
	v_pk_fma_f32 v[130:131], v[96:97], v[112:113], v[184:185]
	global_store_dwordx4 v[136:137], v[130:133], off offset:576

.LBB0_2490:
	s_or_b64 exec, exec, s[8:9]
	v_add_u32_e32 v100, s48, v165
	v_ashrrev_i32_e32 v101, 31, v100
	v_lshlrev_b64 v[102:103], 2, v[100:101]
	v_lshl_add_u64 v[104:105], v[98:99], 0, v[102:103]
	global_load_dwordx4 v[98:101], v[104:105], off
	global_load_dwordx4 v[176:179], v[104:105], off offset:64
	global_load_dwordx4 v[180:183], v[104:105], off offset:512
	global_load_dwordx4 v[184:187], v[104:105], off offset:576
	v_readlane_b32 s8, v255, 10
	v_readlane_b32 s9, v255, 11
	s_waitcnt vmcnt(0) lgkmcnt(0)
	v_pk_fma_f32 v[100:101], v[94:95], v[126:127], v[100:101]
	v_lshl_add_u64 v[96:97], s[8:9], 0, v[96:97]
	v_lshl_add_u64 v[102:103], v[96:97], 0, v[102:103]
	v_pk_fma_f32 v[98:99], v[92:93], v[124:125], v[98:99]
	global_store_dwordx4 v[102:103], v[98:101], off
	s_waitcnt lgkmcnt(0)
	s_nop 0
	v_pk_fma_f32 v[98:99], v[90:91], v[122:123], v[178:179]
	v_pk_fma_f32 v[96:97], v[88:89], v[120:121], v[176:177]
	global_store_dwordx4 v[102:103], v[96:99], off offset:64
	s_waitcnt lgkmcnt(0)
	s_nop 0
	v_pk_fma_f32 v[98:99], v[86:87], v[118:119], v[182:183]
	v_pk_fma_f32 v[96:97], v[84:85], v[116:117], v[180:181]
	global_store_dwordx4 v[102:103], v[96:99], off offset:512
	s_waitcnt lgkmcnt(0)
	s_nop 0
	v_pk_fma_f32 v[98:99], v[82:83], v[114:115], v[186:187]
	v_pk_fma_f32 v[96:97], v[80:81], v[112:113], v[184:185]
	global_store_dwordx4 v[102:103], v[96:99], off offset:576

.LBB0_2496:
	s_or_b64 exec, exec, s[8:9]
	v_add_u32_e32 v84, s48, v165
	v_ashrrev_i32_e32 v85, 31, v84
	v_lshlrev_b64 v[86:87], 2, v[84:85]
	v_lshl_add_u64 v[88:89], v[82:83], 0, v[86:87]
	global_load_dwordx4 v[82:85], v[88:89], off
	global_load_dwordx4 v[176:179], v[88:89], off offset:64
	global_load_dwordx4 v[180:183], v[88:89], off offset:512
	global_load_dwordx4 v[184:187], v[88:89], off offset:576
	v_readlane_b32 s8, v255, 10
	v_readlane_b32 s9, v255, 11
	s_waitcnt vmcnt(0) lgkmcnt(0)
	v_pk_fma_f32 v[84:85], v[78:79], v[126:127], v[84:85]
	v_lshl_add_u64 v[80:81], s[8:9], 0, v[80:81]
	v_lshl_add_u64 v[86:87], v[80:81], 0, v[86:87]
	v_pk_fma_f32 v[82:83], v[76:77], v[124:125], v[82:83]
	global_store_dwordx4 v[86:87], v[82:85], off
	s_waitcnt lgkmcnt(0)
	s_nop 0
	v_pk_fma_f32 v[82:83], v[74:75], v[122:123], v[178:179]
	v_pk_fma_f32 v[80:81], v[72:73], v[120:121], v[176:177]
	global_store_dwordx4 v[86:87], v[80:83], off offset:64
	s_waitcnt lgkmcnt(0)
	s_nop 0
	v_pk_fma_f32 v[82:83], v[70:71], v[118:119], v[182:183]
	v_pk_fma_f32 v[80:81], v[68:69], v[116:117], v[180:181]
	global_store_dwordx4 v[86:87], v[80:83], off offset:512
	s_waitcnt lgkmcnt(0)
	s_nop 0
	v_pk_fma_f32 v[82:83], v[66:67], v[114:115], v[186:187]
	v_pk_fma_f32 v[80:81], v[64:65], v[112:113], v[184:185]
	global_store_dwordx4 v[86:87], v[80:83], off offset:576

.LBB0_2502:
	s_or_b64 exec, exec, s[8:9]
	v_add_u32_e32 v68, s48, v165
	v_ashrrev_i32_e32 v69, 31, v68
	v_lshlrev_b64 v[70:71], 2, v[68:69]
	v_lshl_add_u64 v[72:73], v[66:67], 0, v[70:71]
	global_load_dwordx4 v[66:69], v[72:73], off
	global_load_dwordx4 v[176:179], v[72:73], off offset:64
	global_load_dwordx4 v[180:183], v[72:73], off offset:512
	global_load_dwordx4 v[184:187], v[72:73], off offset:576
	v_readlane_b32 s8, v255, 10
	v_readlane_b32 s9, v255, 11
	s_waitcnt vmcnt(0) lgkmcnt(0)
	v_pk_fma_f32 v[68:69], v[62:63], v[126:127], v[68:69]
	v_lshl_add_u64 v[64:65], s[8:9], 0, v[64:65]
	v_lshl_add_u64 v[70:71], v[64:65], 0, v[70:71]
	v_pk_fma_f32 v[66:67], v[60:61], v[124:125], v[66:67]
	global_store_dwordx4 v[70:71], v[66:69], off
	s_waitcnt lgkmcnt(0)
	s_nop 0
	v_pk_fma_f32 v[66:67], v[58:59], v[122:123], v[178:179]
	v_pk_fma_f32 v[64:65], v[56:57], v[120:121], v[176:177]
	global_store_dwordx4 v[70:71], v[64:67], off offset:64
	s_waitcnt lgkmcnt(0)
	s_nop 0
	v_pk_fma_f32 v[66:67], v[54:55], v[118:119], v[182:183]
	v_pk_fma_f32 v[64:65], v[52:53], v[116:117], v[180:181]
	global_store_dwordx4 v[70:71], v[64:67], off offset:512
	s_waitcnt lgkmcnt(0)
	s_nop 0
	v_pk_fma_f32 v[66:67], v[50:51], v[114:115], v[186:187]
	v_pk_fma_f32 v[64:65], v[48:49], v[112:113], v[184:185]
	global_store_dwordx4 v[70:71], v[64:67], off offset:576

.LBB0_2508:
	s_or_b64 exec, exec, s[8:9]
	v_add_u32_e32 v52, s48, v165
	v_ashrrev_i32_e32 v53, 31, v52
	v_lshlrev_b64 v[54:55], 2, v[52:53]
	v_lshl_add_u64 v[56:57], v[50:51], 0, v[54:55]
	global_load_dwordx4 v[50:53], v[56:57], off
	global_load_dwordx4 v[176:179], v[56:57], off offset:64
	global_load_dwordx4 v[180:183], v[56:57], off offset:512
	global_load_dwordx4 v[184:187], v[56:57], off offset:576
	v_readlane_b32 s8, v255, 10
	v_readlane_b32 s9, v255, 11
	s_waitcnt vmcnt(0) lgkmcnt(0)
	v_pk_fma_f32 v[52:53], v[46:47], v[126:127], v[52:53]
	v_lshl_add_u64 v[48:49], s[8:9], 0, v[48:49]
	v_lshl_add_u64 v[54:55], v[48:49], 0, v[54:55]
	v_pk_fma_f32 v[50:51], v[44:45], v[124:125], v[50:51]
	global_store_dwordx4 v[54:55], v[50:53], off
	s_waitcnt lgkmcnt(0)
	s_nop 0
	v_pk_fma_f32 v[50:51], v[42:43], v[122:123], v[178:179]
	v_pk_fma_f32 v[48:49], v[40:41], v[120:121], v[176:177]
	global_store_dwordx4 v[54:55], v[48:51], off offset:64
	s_waitcnt lgkmcnt(0)
	s_nop 0
	v_pk_fma_f32 v[50:51], v[38:39], v[118:119], v[182:183]
	v_pk_fma_f32 v[48:49], v[36:37], v[116:117], v[180:181]
	global_store_dwordx4 v[54:55], v[48:51], off offset:512
	s_waitcnt lgkmcnt(0)
	s_nop 0
	v_pk_fma_f32 v[50:51], v[34:35], v[114:115], v[186:187]
	v_pk_fma_f32 v[48:49], v[32:33], v[112:113], v[184:185]
	global_store_dwordx4 v[54:55], v[48:51], off offset:576

.LBB0_2514:
	s_or_b64 exec, exec, s[8:9]
	v_add_u32_e32 v36, s48, v165
	v_ashrrev_i32_e32 v37, 31, v36
	v_lshlrev_b64 v[38:39], 2, v[36:37]
	v_lshl_add_u64 v[40:41], v[34:35], 0, v[38:39]
	global_load_dwordx4 v[34:37], v[40:41], off
	global_load_dwordx4 v[176:179], v[40:41], off offset:64
	global_load_dwordx4 v[180:183], v[40:41], off offset:512
	global_load_dwordx4 v[184:187], v[40:41], off offset:576
	v_readlane_b32 s8, v255, 10
	v_readlane_b32 s9, v255, 11
	s_waitcnt vmcnt(0) lgkmcnt(0)
	v_pk_fma_f32 v[36:37], v[30:31], v[126:127], v[36:37]
	v_lshl_add_u64 v[32:33], s[8:9], 0, v[32:33]
	v_lshl_add_u64 v[38:39], v[32:33], 0, v[38:39]
	v_pk_fma_f32 v[34:35], v[28:29], v[124:125], v[34:35]
	global_store_dwordx4 v[38:39], v[34:37], off
	s_waitcnt lgkmcnt(0)
	s_nop 0
	v_pk_fma_f32 v[34:35], v[26:27], v[122:123], v[178:179]
	v_pk_fma_f32 v[32:33], v[24:25], v[120:121], v[176:177]
	global_store_dwordx4 v[38:39], v[32:35], off offset:64
	s_waitcnt lgkmcnt(0)
	s_nop 0
	v_pk_fma_f32 v[34:35], v[22:23], v[118:119], v[182:183]
	v_pk_fma_f32 v[32:33], v[20:21], v[116:117], v[180:181]
	global_store_dwordx4 v[38:39], v[32:35], off offset:512
	s_waitcnt lgkmcnt(0)
	s_nop 0
	v_pk_fma_f32 v[34:35], v[18:19], v[114:115], v[186:187]
	v_pk_fma_f32 v[32:33], v[16:17], v[112:113], v[184:185]
	global_store_dwordx4 v[38:39], v[32:35], off offset:576

.LBB0_2520:
	s_or_b64 exec, exec, s[8:9]
	v_add_u32_e32 v20, s48, v165
	v_ashrrev_i32_e32 v21, 31, v20
	v_lshlrev_b64 v[22:23], 2, v[20:21]
	v_lshl_add_u64 v[24:25], v[18:19], 0, v[22:23]
	global_load_dwordx4 v[18:21], v[24:25], off
	global_load_dwordx4 v[176:179], v[24:25], off offset:64
	global_load_dwordx4 v[180:183], v[24:25], off offset:512
	global_load_dwordx4 v[184:187], v[24:25], off offset:576
	v_readlane_b32 s8, v255, 10
	v_readlane_b32 s9, v255, 11
	s_waitcnt vmcnt(0) lgkmcnt(0)
	v_pk_fma_f32 v[20:21], v[14:15], v[126:127], v[20:21]
	v_lshl_add_u64 v[16:17], s[8:9], 0, v[16:17]
	v_lshl_add_u64 v[22:23], v[16:17], 0, v[22:23]
	v_pk_fma_f32 v[18:19], v[12:13], v[124:125], v[18:19]
	global_store_dwordx4 v[22:23], v[18:21], off
	s_waitcnt lgkmcnt(0)
	s_nop 0
	v_pk_fma_f32 v[18:19], v[10:11], v[122:123], v[178:179]
	v_pk_fma_f32 v[16:17], v[8:9], v[120:121], v[176:177]
	global_store_dwordx4 v[22:23], v[16:19], off offset:64
	s_waitcnt lgkmcnt(0)
	s_nop 0
	v_pk_fma_f32 v[18:19], v[6:7], v[118:119], v[182:183]
	v_pk_fma_f32 v[16:17], v[4:5], v[116:117], v[180:181]
	global_store_dwordx4 v[22:23], v[16:19], off offset:512
	s_waitcnt lgkmcnt(0)
	s_nop 0
	v_pk_fma_f32 v[18:19], v[2:3], v[114:115], v[186:187]
	v_pk_fma_f32 v[16:17], v[0:1], v[112:113], v[184:185]
	global_store_dwordx4 v[22:23], v[16:19], off offset:576

.LBB0_2565:
	s_or_b64 exec, exec, s[8:9]
	v_add_u32_e32 v154, s44, v154
	v_ashrrev_i32_e32 v155, 31, v154
	v_lshlrev_b64 v[154:155], 2, v[154:155]
	v_lshl_add_u64 v[160:161], v[160:161], 0, v[154:155]
	global_load_dwordx4 v[166:169], v[160:161], off
	global_load_dwordx4 v[172:175], v[160:161], off offset:64
	global_load_dwordx4 v[176:179], v[160:161], off offset:512
	global_load_dwordx4 v[180:183], v[160:161], off offset:576
	v_readlane_b32 s8, v255, 10
	v_readlane_b32 s9, v255, 11
	s_waitcnt vmcnt(0) lgkmcnt(0)
	v_pk_fma_f32 v[126:127], v[126:127], v[144:145], v[168:169]
	v_lshl_add_u64 v[158:159], s[8:9], 0, v[158:159]
	v_lshl_add_u64 v[158:159], v[158:159], 0, v[154:155]
	v_pk_fma_f32 v[124:125], v[124:125], v[142:143], v[166:167]
	global_store_dwordx4 v[158:159], v[124:127], off
	s_movk_i32 s8, 0x3fff
	s_waitcnt lgkmcnt(0)
	v_pk_fma_f32 v[122:123], v[122:123], v[140:141], v[174:175]
	v_pk_fma_f32 v[120:121], v[120:121], v[138:139], v[172:173]
	global_store_dwordx4 v[158:159], v[120:123], off offset:64
	s_waitcnt lgkmcnt(0)
	v_pk_fma_f32 v[118:119], v[118:119], v[136:137], v[178:179]
	v_pk_fma_f32 v[116:117], v[116:117], v[134:135], v[176:177]
	global_store_dwordx4 v[158:159], v[116:119], off offset:512
	s_waitcnt lgkmcnt(0)
	v_pk_fma_f32 v[114:115], v[114:115], v[132:133], v[182:183]
	v_add_u32_e32 v116, 16, v156
	v_pk_fma_f32 v[112:113], v[112:113], v[130:131], v[180:181]
	v_cmp_lt_i32_e32 vcc, s8, v116
	global_store_dwordx4 v[158:159], v[112:115], off offset:576
	s_and_saveexec_b64 s[8:9], vcc
	s_xor_b64 s[8:9], exec, s[8:9]
	s_cbranch_execz .LBB0_2567
	v_add_u32_e32 v112, 0xffffc010, v156
	v_mov_b32_e32 v113, v129
	v_readlane_b32 s38, v255, 14
	v_lshlrev_b64 v[112:113], 12, v[112:113]
	v_readlane_b32 s39, v255, 15
	v_mov_b32_e32 v117, v129
	s_nop 0
	v_lshl_add_u64 v[114:115], s[38:39], 0, v[112:113]
	v_lshlrev_b64 v[112:113], 12, v[116:117]

.LBB0_2569:
	s_or_b64 exec, exec, s[8:9]
	v_lshl_add_u64 v[118:119], v[114:115], 0, v[154:155]
	global_load_dwordx4 v[114:117], v[118:119], off
	global_load_dwordx4 v[172:175], v[118:119], off offset:64
	global_load_dwordx4 v[176:179], v[118:119], off offset:512
	global_load_dwordx4 v[180:183], v[118:119], off offset:576
	v_readlane_b32 s8, v255, 10
	v_readlane_b32 s9, v255, 11
	s_waitcnt vmcnt(0) lgkmcnt(0)
	v_pk_fma_f32 v[108:109], v[108:109], v[142:143], v[114:115]
	v_lshl_add_u64 v[112:113], s[8:9], 0, v[112:113]
	v_lshl_add_u64 v[112:113], v[112:113], 0, v[154:155]
	v_pk_fma_f32 v[110:111], v[110:111], v[144:145], v[116:117]
	global_store_dwordx4 v[112:113], v[108:111], off
	s_movk_i32 s8, 0x3fff
	s_waitcnt lgkmcnt(0)
	v_pk_fma_f32 v[104:105], v[104:105], v[138:139], v[172:173]
	v_pk_fma_f32 v[106:107], v[106:107], v[140:141], v[174:175]
	global_store_dwordx4 v[112:113], v[104:107], off offset:64
	s_waitcnt lgkmcnt(0)
	v_pk_fma_f32 v[100:101], v[100:101], v[134:135], v[176:177]
	v_pk_fma_f32 v[102:103], v[102:103], v[136:137], v[178:179]
	global_store_dwordx4 v[112:113], v[100:103], off offset:512
	s_waitcnt lgkmcnt(0)
	v_pk_fma_f32 v[96:97], v[96:97], v[130:131], v[180:181]
	v_add_u32_e32 v100, 32, v156
	v_pk_fma_f32 v[98:99], v[98:99], v[132:133], v[182:183]
	v_cmp_lt_i32_e32 vcc, s8, v100
	global_store_dwordx4 v[112:113], v[96:99], off offset:576
	s_and_saveexec_b64 s[8:9], vcc
	s_xor_b64 s[8:9], exec, s[8:9]
	s_cbranch_execz .LBB0_2571
	v_add_u32_e32 v96, 0xffffc020, v156
	v_mov_b32_e32 v97, v129
	v_readlane_b32 s38, v255, 14
	v_lshlrev_b64 v[96:97], 12, v[96:97]
	v_readlane_b32 s39, v255, 15
	v_mov_b32_e32 v101, v129
	s_nop 0
	v_lshl_add_u64 v[98:99], s[38:39], 0, v[96:97]
	v_lshlrev_b64 v[96:97], 12, v[100:101]

.LBB0_2573:
	s_or_b64 exec, exec, s[8:9]
	v_lshl_add_u64 v[102:103], v[98:99], 0, v[154:155]
	global_load_dwordx4 v[98:101], v[102:103], off
	global_load_dwordx4 v[172:175], v[102:103], off offset:64
	global_load_dwordx4 v[176:179], v[102:103], off offset:512
	global_load_dwordx4 v[180:183], v[102:103], off offset:576
	v_readlane_b32 s8, v255, 10
	v_readlane_b32 s9, v255, 11
	s_waitcnt vmcnt(0) lgkmcnt(0)
	v_pk_fma_f32 v[92:93], v[92:93], v[142:143], v[98:99]
	v_lshl_add_u64 v[96:97], s[8:9], 0, v[96:97]
	v_lshl_add_u64 v[96:97], v[96:97], 0, v[154:155]
	v_pk_fma_f32 v[94:95], v[94:95], v[144:145], v[100:101]
	global_store_dwordx4 v[96:97], v[92:95], off
	s_movk_i32 s8, 0x3fff
	s_waitcnt lgkmcnt(0)
	v_pk_fma_f32 v[88:89], v[88:89], v[138:139], v[172:173]
	v_pk_fma_f32 v[90:91], v[90:91], v[140:141], v[174:175]
	global_store_dwordx4 v[96:97], v[88:91], off offset:64
	s_waitcnt lgkmcnt(0)
	v_pk_fma_f32 v[84:85], v[84:85], v[134:135], v[176:177]
	v_pk_fma_f32 v[86:87], v[86:87], v[136:137], v[178:179]
	global_store_dwordx4 v[96:97], v[84:87], off offset:512
	s_waitcnt lgkmcnt(0)
	v_pk_fma_f32 v[80:81], v[80:81], v[130:131], v[180:181]
	v_add_u32_e32 v84, 48, v156
	v_pk_fma_f32 v[82:83], v[82:83], v[132:133], v[182:183]
	v_cmp_lt_i32_e32 vcc, s8, v84
	global_store_dwordx4 v[96:97], v[80:83], off offset:576
	s_and_saveexec_b64 s[8:9], vcc
	s_xor_b64 s[8:9], exec, s[8:9]
	s_cbranch_execz .LBB0_2575
	v_add_u32_e32 v80, 0xffffc030, v156
	v_mov_b32_e32 v81, v129
	v_readlane_b32 s38, v255, 14
	v_lshlrev_b64 v[80:81], 12, v[80:81]
	v_readlane_b32 s39, v255, 15
	v_mov_b32_e32 v85, v129
	s_nop 0
	v_lshl_add_u64 v[82:83], s[38:39], 0, v[80:81]
	v_lshlrev_b64 v[80:81], 12, v[84:85]

.LBB0_2577:
	s_or_b64 exec, exec, s[8:9]
	v_lshl_add_u64 v[86:87], v[82:83], 0, v[154:155]
	global_load_dwordx4 v[82:85], v[86:87], off
	global_load_dwordx4 v[172:175], v[86:87], off offset:64
	global_load_dwordx4 v[176:179], v[86:87], off offset:512
	global_load_dwordx4 v[180:183], v[86:87], off offset:576
	v_readlane_b32 s8, v255, 10
	v_readlane_b32 s9, v255, 11
	s_waitcnt vmcnt(0) lgkmcnt(0)
	v_pk_fma_f32 v[76:77], v[76:77], v[142:143], v[82:83]
	v_lshl_add_u64 v[80:81], s[8:9], 0, v[80:81]
	v_lshl_add_u64 v[80:81], v[80:81], 0, v[154:155]
	v_pk_fma_f32 v[78:79], v[78:79], v[144:145], v[84:85]
	global_store_dwordx4 v[80:81], v[76:79], off
	s_movk_i32 s8, 0x3fff
	s_waitcnt lgkmcnt(0)
	v_pk_fma_f32 v[72:73], v[72:73], v[138:139], v[172:173]
	v_pk_fma_f32 v[74:75], v[74:75], v[140:141], v[174:175]
	global_store_dwordx4 v[80:81], v[72:75], off offset:64
	s_waitcnt lgkmcnt(0)
	v_pk_fma_f32 v[68:69], v[68:69], v[134:135], v[176:177]
	v_pk_fma_f32 v[70:71], v[70:71], v[136:137], v[178:179]
	global_store_dwordx4 v[80:81], v[68:71], off offset:512
	s_waitcnt lgkmcnt(0)
	v_pk_fma_f32 v[64:65], v[64:65], v[130:131], v[180:181]
	v_add_u32_e32 v68, 0x80, v156
	v_pk_fma_f32 v[66:67], v[66:67], v[132:133], v[182:183]
	v_cmp_lt_i32_e32 vcc, s8, v68
	global_store_dwordx4 v[80:81], v[64:67], off offset:576
	s_and_saveexec_b64 s[8:9], vcc
	s_xor_b64 s[8:9], exec, s[8:9]
	s_cbranch_execz .LBB0_2579
	v_add_u32_e32 v64, 0xffffc080, v156
	v_mov_b32_e32 v65, v129
	v_readlane_b32 s38, v255, 14
	v_lshlrev_b64 v[64:65], 12, v[64:65]
	v_readlane_b32 s39, v255, 15
	v_mov_b32_e32 v69, v129
	s_nop 0
	v_lshl_add_u64 v[66:67], s[38:39], 0, v[64:65]
	v_lshlrev_b64 v[64:65], 12, v[68:69]

.LBB0_2581:
	s_or_b64 exec, exec, s[8:9]
	v_lshl_add_u64 v[70:71], v[66:67], 0, v[154:155]
	global_load_dwordx4 v[66:69], v[70:71], off
	global_load_dwordx4 v[172:175], v[70:71], off offset:64
	global_load_dwordx4 v[176:179], v[70:71], off offset:512
	global_load_dwordx4 v[180:183], v[70:71], off offset:576
	v_readlane_b32 s8, v255, 10
	v_readlane_b32 s9, v255, 11
	s_waitcnt vmcnt(0) lgkmcnt(0)
	v_pk_fma_f32 v[60:61], v[60:61], v[142:143], v[66:67]
	v_lshl_add_u64 v[64:65], s[8:9], 0, v[64:65]
	v_lshl_add_u64 v[64:65], v[64:65], 0, v[154:155]
	v_pk_fma_f32 v[62:63], v[62:63], v[144:145], v[68:69]
	global_store_dwordx4 v[64:65], v[60:63], off
	s_movk_i32 s8, 0x3fff
	s_waitcnt lgkmcnt(0)
	v_pk_fma_f32 v[56:57], v[56:57], v[138:139], v[172:173]
	v_pk_fma_f32 v[58:59], v[58:59], v[140:141], v[174:175]
	global_store_dwordx4 v[64:65], v[56:59], off offset:64
	s_waitcnt lgkmcnt(0)
	v_pk_fma_f32 v[52:53], v[52:53], v[134:135], v[176:177]
	v_pk_fma_f32 v[54:55], v[54:55], v[136:137], v[178:179]
	global_store_dwordx4 v[64:65], v[52:55], off offset:512
	s_waitcnt lgkmcnt(0)
	v_pk_fma_f32 v[48:49], v[48:49], v[130:131], v[180:181]
	v_add_u32_e32 v52, 0x90, v156
	v_pk_fma_f32 v[50:51], v[50:51], v[132:133], v[182:183]
	v_cmp_lt_i32_e32 vcc, s8, v52
	global_store_dwordx4 v[64:65], v[48:51], off offset:576
	s_and_saveexec_b64 s[8:9], vcc
	s_xor_b64 s[8:9], exec, s[8:9]
	s_cbranch_execz .LBB0_2583
	v_add_u32_e32 v48, 0xffffc090, v156
	v_mov_b32_e32 v49, v129
	v_readlane_b32 s38, v255, 14
	v_lshlrev_b64 v[48:49], 12, v[48:49]
	v_readlane_b32 s39, v255, 15
	v_mov_b32_e32 v53, v129
	s_nop 0
	v_lshl_add_u64 v[50:51], s[38:39], 0, v[48:49]
	v_lshlrev_b64 v[48:49], 12, v[52:53]

.LBB0_2585:
	s_or_b64 exec, exec, s[8:9]
	v_lshl_add_u64 v[54:55], v[50:51], 0, v[154:155]
	global_load_dwordx4 v[50:53], v[54:55], off
	global_load_dwordx4 v[172:175], v[54:55], off offset:64
	global_load_dwordx4 v[176:179], v[54:55], off offset:512
	global_load_dwordx4 v[180:183], v[54:55], off offset:576
	v_readlane_b32 s8, v255, 10
	v_readlane_b32 s9, v255, 11
	s_waitcnt vmcnt(0) lgkmcnt(0)
	v_pk_fma_f32 v[44:45], v[44:45], v[142:143], v[50:51]
	v_lshl_add_u64 v[48:49], s[8:9], 0, v[48:49]
	v_lshl_add_u64 v[48:49], v[48:49], 0, v[154:155]
	v_pk_fma_f32 v[46:47], v[46:47], v[144:145], v[52:53]
	global_store_dwordx4 v[48:49], v[44:47], off
	s_movk_i32 s8, 0x3fff
	s_waitcnt lgkmcnt(0)
	v_pk_fma_f32 v[40:41], v[40:41], v[138:139], v[172:173]
	v_pk_fma_f32 v[42:43], v[42:43], v[140:141], v[174:175]
	global_store_dwordx4 v[48:49], v[40:43], off offset:64
	s_waitcnt lgkmcnt(0)
	v_pk_fma_f32 v[36:37], v[36:37], v[134:135], v[176:177]
	v_pk_fma_f32 v[38:39], v[38:39], v[136:137], v[178:179]
	global_store_dwordx4 v[48:49], v[36:39], off offset:512
	s_waitcnt lgkmcnt(0)
	v_pk_fma_f32 v[32:33], v[32:33], v[130:131], v[180:181]
	v_add_u32_e32 v36, 0xa0, v156
	v_pk_fma_f32 v[34:35], v[34:35], v[132:133], v[182:183]
	v_cmp_lt_i32_e32 vcc, s8, v36
	global_store_dwordx4 v[48:49], v[32:35], off offset:576
	s_and_saveexec_b64 s[8:9], vcc
	s_xor_b64 s[8:9], exec, s[8:9]
	s_cbranch_execz .LBB0_2587
	v_add_u32_e32 v32, 0xffffc0a0, v156
	v_mov_b32_e32 v33, v129
	v_readlane_b32 s38, v255, 14
	v_lshlrev_b64 v[32:33], 12, v[32:33]
	v_readlane_b32 s39, v255, 15
	v_mov_b32_e32 v37, v129
	s_nop 0
	v_lshl_add_u64 v[34:35], s[38:39], 0, v[32:33]
	v_lshlrev_b64 v[32:33], 12, v[36:37]

.LBB0_2589:
	s_or_b64 exec, exec, s[8:9]
	v_lshl_add_u64 v[38:39], v[34:35], 0, v[154:155]
	global_load_dwordx4 v[34:37], v[38:39], off
	global_load_dwordx4 v[172:175], v[38:39], off offset:64
	global_load_dwordx4 v[176:179], v[38:39], off offset:512
	global_load_dwordx4 v[180:183], v[38:39], off offset:576
	v_readlane_b32 s8, v255, 10
	v_readlane_b32 s9, v255, 11
	s_waitcnt vmcnt(0) lgkmcnt(0)
	v_pk_fma_f32 v[28:29], v[28:29], v[142:143], v[34:35]
	v_lshl_add_u64 v[32:33], s[8:9], 0, v[32:33]
	v_lshl_add_u64 v[32:33], v[32:33], 0, v[154:155]
	v_pk_fma_f32 v[30:31], v[30:31], v[144:145], v[36:37]
	global_store_dwordx4 v[32:33], v[28:31], off
	s_movk_i32 s8, 0x3fff
	s_waitcnt lgkmcnt(0)
	v_pk_fma_f32 v[24:25], v[24:25], v[138:139], v[172:173]
	v_pk_fma_f32 v[26:27], v[26:27], v[140:141], v[174:175]
	global_store_dwordx4 v[32:33], v[24:27], off offset:64
	s_waitcnt lgkmcnt(0)
	v_pk_fma_f32 v[20:21], v[20:21], v[134:135], v[176:177]
	v_pk_fma_f32 v[22:23], v[22:23], v[136:137], v[178:179]
	global_store_dwordx4 v[32:33], v[20:23], off offset:512
	s_waitcnt lgkmcnt(0)
	v_pk_fma_f32 v[16:17], v[16:17], v[130:131], v[180:181]
	v_add_u32_e32 v20, 0xb0, v156
	v_pk_fma_f32 v[18:19], v[18:19], v[132:133], v[182:183]
	v_cmp_lt_i32_e32 vcc, s8, v20
	global_store_dwordx4 v[32:33], v[16:19], off offset:576
	s_and_saveexec_b64 s[8:9], vcc
	s_xor_b64 s[8:9], exec, s[8:9]
	s_cbranch_execz .LBB0_2591
	v_add_u32_e32 v16, 0xffffc0b0, v156
	v_mov_b32_e32 v17, v129
	v_readlane_b32 s38, v255, 14
	v_lshlrev_b64 v[16:17], 12, v[16:17]
	v_readlane_b32 s39, v255, 15
	v_mov_b32_e32 v21, v129
	s_nop 0
	v_lshl_add_u64 v[18:19], s[38:39], 0, v[16:17]
	v_lshlrev_b64 v[16:17], 12, v[20:21]
